# GEMM main loops: LDS-DMA issue rebalanced across load segments (2/6/2/6 -> 2/4/4/6 pieces), segment-2 wait vmcnt(6); on top of MLA body + phase-0 rotation
# speedup vs baseline: 1.0021x; 1.0021x over previous
.LBB0_188:
	s_add_u32 s24, s22, 0xfffc0080
	s_addc_u32 s25, s23, -1
	s_add_i32 s51, 0, 0x10000
	s_cmp_eq_u32 s50, 12
	s_cselect_b32 s27, s3, s25
	s_cselect_b32 s26, s15, s24
	v_add_u32_e32 v142, s51, v144
	s_cselect_b32 s25, s13, s49
	s_cselect_b32 s24, s21, s48
	s_add_i32 s54, 0, 0x14000
	ds_read_b128 v[138:141], v142
	ds_read_b128 v[146:149], v142 offset:1024
	ds_read_b128 v[150:153], v142 offset:2048
	ds_read_b128 v[154:157], v142 offset:3072
	v_add_u32_e32 v142, s54, v144
	ds_read_b128 v[158:161], v142
	ds_read_b128 v[162:165], v142 offset:1024
	ds_read_b128 v[166:169], v142 offset:2048
	ds_read_b128 v[170:173], v142 offset:3072
	v_lshl_add_u64 v[142:143], s[22:23], 0, v[136:137]
	s_add_i32 m0, s37, 0xc000
	ds_read_b128 v[174:177], v145
	ds_read_b128 v[178:181], v145 offset:1024
	ds_read_b128 v[182:185], v145 offset:2048
	ds_read_b128 v[186:189], v145 offset:3072
	ds_read_b128 v[190:193], v145 offset:4096
	ds_read_b128 v[194:197], v145 offset:5120
	ds_read_b128 v[198:201], v145 offset:6144
	ds_read_b128 v[202:205], v145 offset:7168
	global_load_lds_dwordx4 v[142:143], off
	v_lshl_add_u64 v[142:143], s[22:23], 0, v[134:135]
	s_add_i32 m0, s37, 0xe000
	s_nop 0
	global_load_lds_dwordx4 v[142:143], off
	s_waitcnt vmcnt(8)
	s_waitcnt lgkmcnt(0)
	s_barrier
	s_setprio 1
	s_waitcnt lgkmcnt(0)
	v_mfma_f32_16x16x32_bf16 v[124:127], v[138:141], v[174:177], v[124:127]
	v_mfma_f32_16x16x32_bf16 v[120:123], v[150:153], v[174:177], v[120:123]
	v_mfma_f32_16x16x32_bf16 v[112:115], v[138:141], v[182:185], v[112:115]
	v_mfma_f32_16x16x32_bf16 v[104:107], v[150:153], v[182:185], v[104:107]
	v_mfma_f32_16x16x32_bf16 v[96:99], v[138:141], v[190:193], v[96:99]
	v_mfma_f32_16x16x32_bf16 v[88:91], v[150:153], v[190:193], v[88:91]
	v_mfma_f32_16x16x32_bf16 v[80:83], v[138:141], v[198:201], v[80:83]
	v_mfma_f32_16x16x32_bf16 v[72:75], v[150:153], v[198:201], v[72:75]
	v_mfma_f32_16x16x32_bf16 v[124:127], v[146:149], v[178:181], v[124:127]
	v_mfma_f32_16x16x32_bf16 v[120:123], v[154:157], v[178:181], v[120:123]
	v_mfma_f32_16x16x32_bf16 v[112:115], v[146:149], v[186:189], v[112:115]
	v_mfma_f32_16x16x32_bf16 v[104:107], v[154:157], v[186:189], v[104:107]
	v_mfma_f32_16x16x32_bf16 v[96:99], v[146:149], v[194:197], v[96:99]
	v_mfma_f32_16x16x32_bf16 v[88:91], v[154:157], v[194:197], v[88:91]
	v_mfma_f32_16x16x32_bf16 v[80:83], v[146:149], v[202:205], v[80:83]
	v_mfma_f32_16x16x32_bf16 v[72:75], v[154:157], v[202:205], v[72:75]
	s_setprio 0
	s_setprio 1
	v_mfma_f32_16x16x32_bf16 v[116:119], v[158:161], v[174:177], v[116:119]
	v_mfma_f32_16x16x32_bf16 v[108:111], v[166:169], v[174:177], v[108:111]
	v_mfma_f32_16x16x32_bf16 v[100:103], v[158:161], v[182:185], v[100:103]
	v_mfma_f32_16x16x32_bf16 v[92:95], v[166:169], v[182:185], v[92:95]
	v_mfma_f32_16x16x32_bf16 v[84:87], v[158:161], v[190:193], v[84:87]
	v_mfma_f32_16x16x32_bf16 v[76:79], v[166:169], v[190:193], v[76:79]
	v_mfma_f32_16x16x32_bf16 v[68:71], v[158:161], v[198:201], v[68:71]
	v_mfma_f32_16x16x32_bf16 v[64:67], v[166:169], v[198:201], v[64:67]
	v_mfma_f32_16x16x32_bf16 v[116:119], v[162:165], v[178:181], v[116:119]
	v_mfma_f32_16x16x32_bf16 v[108:111], v[170:173], v[178:181], v[108:111]
	v_mfma_f32_16x16x32_bf16 v[100:103], v[162:165], v[186:189], v[100:103]
	v_mfma_f32_16x16x32_bf16 v[92:95], v[170:173], v[186:189], v[92:95]
	v_mfma_f32_16x16x32_bf16 v[84:87], v[162:165], v[194:197], v[84:87]
	v_mfma_f32_16x16x32_bf16 v[76:79], v[170:173], v[194:197], v[76:79]
	v_mfma_f32_16x16x32_bf16 v[68:71], v[162:165], v[202:205], v[68:71]
	v_mfma_f32_16x16x32_bf16 v[64:67], v[170:173], v[202:205], v[64:67]
	s_setprio 0
	s_barrier
	s_add_i32 s51, s51, s36
	v_lshl_add_u64 v[142:143], s[24:25], 0, v[232:233]
	s_mov_b32 m0, s51
	ds_read_b128 v[174:177], v145 offset:16384
	ds_read_b128 v[178:181], v145 offset:17408
	ds_read_b128 v[182:185], v145 offset:18432
	ds_read_b128 v[186:189], v145 offset:19456
	ds_read_b128 v[190:193], v145 offset:20480
	ds_read_b128 v[194:197], v145 offset:21504
	ds_read_b128 v[198:201], v145 offset:22528
	ds_read_b128 v[202:205], v145 offset:23552
	global_load_lds_dwordx4 v[142:143], off
	s_add_i32 m0, s51, 0x2000
	s_add_u32 s52, s24, 0x40000
	v_lshl_add_u64 v[206:207], s[24:25], 0, v[132:133]
	s_addc_u32 s53, s25, 0
	s_add_i32 s51, s54, s36
	global_load_lds_dwordx4 v[206:207], off
	v_lshl_add_u64 v[208:209], s[52:53], 0, v[232:233]
	s_mov_b32 m0, s51
	v_lshl_add_u64 v[210:211], s[26:27], 0, v[130:131]
	global_load_lds_dwordx4 v[208:209], off
	v_lshl_add_u64 v[208:209], s[52:53], 0, v[132:133]
	s_add_i32 m0, s51, 0x2000
	s_nop 0
	global_load_lds_dwordx4 v[208:209], off
	v_lshl_add_u64 v[208:209], s[26:27], 0, v[128:129]
	s_waitcnt vmcnt(6)
	s_waitcnt lgkmcnt(0)
	s_barrier
	s_setprio 1
	s_waitcnt lgkmcnt(0)
	v_mfma_f32_16x16x32_bf16 v[60:63], v[138:141], v[174:177], v[60:63]
	v_mfma_f32_16x16x32_bf16 v[56:59], v[150:153], v[174:177], v[56:59]
	v_mfma_f32_16x16x32_bf16 v[48:51], v[138:141], v[182:185], v[48:51]
	v_mfma_f32_16x16x32_bf16 v[40:43], v[150:153], v[182:185], v[40:43]
	v_mfma_f32_16x16x32_bf16 v[32:35], v[138:141], v[190:193], v[32:35]
	v_mfma_f32_16x16x32_bf16 v[24:27], v[150:153], v[190:193], v[24:27]
	v_mfma_f32_16x16x32_bf16 v[16:19], v[138:141], v[198:201], v[16:19]
	v_mfma_f32_16x16x32_bf16 v[8:11], v[150:153], v[198:201], v[8:11]
	v_mfma_f32_16x16x32_bf16 v[60:63], v[146:149], v[178:181], v[60:63]
	v_mfma_f32_16x16x32_bf16 v[56:59], v[154:157], v[178:181], v[56:59]
	v_mfma_f32_16x16x32_bf16 v[48:51], v[146:149], v[186:189], v[48:51]
	v_mfma_f32_16x16x32_bf16 v[40:43], v[154:157], v[186:189], v[40:43]
	v_mfma_f32_16x16x32_bf16 v[32:35], v[146:149], v[194:197], v[32:35]
	v_mfma_f32_16x16x32_bf16 v[24:27], v[154:157], v[194:197], v[24:27]
	v_mfma_f32_16x16x32_bf16 v[16:19], v[146:149], v[202:205], v[16:19]
	v_mfma_f32_16x16x32_bf16 v[8:11], v[154:157], v[202:205], v[8:11]
	s_setprio 0
	s_setprio 1
	v_mfma_f32_16x16x32_bf16 v[52:55], v[158:161], v[174:177], v[52:55]
	v_mfma_f32_16x16x32_bf16 v[44:47], v[166:169], v[174:177], v[44:47]
	v_mfma_f32_16x16x32_bf16 v[36:39], v[158:161], v[182:185], v[36:39]
	v_mfma_f32_16x16x32_bf16 v[28:31], v[166:169], v[182:185], v[28:31]
	v_mfma_f32_16x16x32_bf16 v[20:23], v[158:161], v[190:193], v[20:23]
	v_mfma_f32_16x16x32_bf16 v[12:15], v[166:169], v[190:193], v[12:15]
	v_mfma_f32_16x16x32_bf16 v[4:7], v[158:161], v[198:201], v[4:7]
	v_mfma_f32_16x16x32_bf16 v[0:3], v[166:169], v[198:201], v[0:3]
	v_mfma_f32_16x16x32_bf16 v[52:55], v[162:165], v[178:181], v[52:55]
	v_mfma_f32_16x16x32_bf16 v[44:47], v[170:173], v[178:181], v[44:47]
	v_mfma_f32_16x16x32_bf16 v[36:39], v[162:165], v[186:189], v[36:39]
	v_mfma_f32_16x16x32_bf16 v[28:31], v[170:173], v[186:189], v[28:31]
	v_mfma_f32_16x16x32_bf16 v[20:23], v[162:165], v[194:197], v[20:23]
	v_mfma_f32_16x16x32_bf16 v[12:15], v[170:173], v[194:197], v[12:15]
	v_mfma_f32_16x16x32_bf16 v[4:7], v[162:165], v[202:205], v[4:7]
	v_mfma_f32_16x16x32_bf16 v[0:3], v[170:173], v[202:205], v[0:3]
	s_setprio 0
	s_barrier
	s_add_i32 s51, 0, 0x18000
	s_add_i32 s52, 0, 0x1c000
	v_add_u32_e32 v154, s51, v144
	v_add_u32_e32 v170, s52, v144
	ds_read_b128 v[138:141], v154
	ds_read_b128 v[146:149], v154 offset:1024
	ds_read_b128 v[150:153], v154 offset:2048
	ds_read_b128 v[154:157], v154 offset:3072
	ds_read_b128 v[158:161], v170
	ds_read_b128 v[162:165], v170 offset:1024
	ds_read_b128 v[166:169], v170 offset:2048
	ds_read_b128 v[170:173], v170 offset:3072
	s_add_u32 s26, s26, 0x40000
	s_addc_u32 s27, s27, 0
	s_mov_b32 m0, s37
	s_nop 0
	global_load_lds_dwordx4 v[208:209], off
	s_mov_b32 m0, s38
	s_nop 0
	global_load_lds_dwordx4 v[210:211], off
	s_mov_b32 m0, s39
	v_lshl_add_u64 v[212:213], s[26:27], 0, v[128:129]
	ds_read_b128 v[174:177], v145 offset:32768
	ds_read_b128 v[178:181], v145 offset:33792
	ds_read_b128 v[182:185], v145 offset:34816
	ds_read_b128 v[186:189], v145 offset:35840
	ds_read_b128 v[190:193], v145 offset:36864
	ds_read_b128 v[194:197], v145 offset:37888
	ds_read_b128 v[198:201], v145 offset:38912
	ds_read_b128 v[202:205], v145 offset:39936
	global_load_lds_dwordx4 v[212:213], off
	v_lshl_add_u64 v[212:213], s[26:27], 0, v[130:131]
	s_mov_b32 m0, s40
	s_nop 0
	global_load_lds_dwordx4 v[212:213], off
	s_waitcnt vmcnt(8)
	s_waitcnt lgkmcnt(0)
	s_barrier
	s_setprio 1
	s_waitcnt lgkmcnt(0)
	v_mfma_f32_16x16x32_bf16 v[124:127], v[138:141], v[174:177], v[124:127]
	v_mfma_f32_16x16x32_bf16 v[120:123], v[150:153], v[174:177], v[120:123]
	v_mfma_f32_16x16x32_bf16 v[112:115], v[138:141], v[182:185], v[112:115]
	v_mfma_f32_16x16x32_bf16 v[104:107], v[150:153], v[182:185], v[104:107]
	v_mfma_f32_16x16x32_bf16 v[96:99], v[138:141], v[190:193], v[96:99]
	v_mfma_f32_16x16x32_bf16 v[88:91], v[150:153], v[190:193], v[88:91]
	v_mfma_f32_16x16x32_bf16 v[80:83], v[138:141], v[198:201], v[80:83]
	v_mfma_f32_16x16x32_bf16 v[72:75], v[150:153], v[198:201], v[72:75]
	v_mfma_f32_16x16x32_bf16 v[124:127], v[146:149], v[178:181], v[124:127]
	v_mfma_f32_16x16x32_bf16 v[120:123], v[154:157], v[178:181], v[120:123]
	v_mfma_f32_16x16x32_bf16 v[112:115], v[146:149], v[186:189], v[112:115]
	v_mfma_f32_16x16x32_bf16 v[104:107], v[154:157], v[186:189], v[104:107]
	v_mfma_f32_16x16x32_bf16 v[96:99], v[146:149], v[194:197], v[96:99]
	v_mfma_f32_16x16x32_bf16 v[88:91], v[154:157], v[194:197], v[88:91]
	v_mfma_f32_16x16x32_bf16 v[80:83], v[146:149], v[202:205], v[80:83]
	v_mfma_f32_16x16x32_bf16 v[72:75], v[154:157], v[202:205], v[72:75]
	s_setprio 0
	s_setprio 1
	v_mfma_f32_16x16x32_bf16 v[116:119], v[158:161], v[174:177], v[116:119]
	v_mfma_f32_16x16x32_bf16 v[108:111], v[166:169], v[174:177], v[108:111]
	v_mfma_f32_16x16x32_bf16 v[100:103], v[158:161], v[182:185], v[100:103]
	v_mfma_f32_16x16x32_bf16 v[92:95], v[166:169], v[182:185], v[92:95]
	v_mfma_f32_16x16x32_bf16 v[84:87], v[158:161], v[190:193], v[84:87]
	v_mfma_f32_16x16x32_bf16 v[76:79], v[166:169], v[190:193], v[76:79]
	v_mfma_f32_16x16x32_bf16 v[68:71], v[158:161], v[198:201], v[68:71]
	v_mfma_f32_16x16x32_bf16 v[64:67], v[166:169], v[198:201], v[64:67]
	v_mfma_f32_16x16x32_bf16 v[116:119], v[162:165], v[178:181], v[116:119]
	v_mfma_f32_16x16x32_bf16 v[108:111], v[170:173], v[178:181], v[108:111]
	v_mfma_f32_16x16x32_bf16 v[100:103], v[162:165], v[186:189], v[100:103]
	v_mfma_f32_16x16x32_bf16 v[92:95], v[170:173], v[186:189], v[92:95]
	v_mfma_f32_16x16x32_bf16 v[84:87], v[162:165], v[194:197], v[84:87]
	v_mfma_f32_16x16x32_bf16 v[76:79], v[170:173], v[194:197], v[76:79]
	v_mfma_f32_16x16x32_bf16 v[68:71], v[162:165], v[202:205], v[68:71]
	v_mfma_f32_16x16x32_bf16 v[64:67], v[170:173], v[202:205], v[64:67]
	s_setprio 0
	s_barrier
	s_add_i32 s26, s51, s36
	v_lshl_add_u64 v[142:143], v[142:143], 0, s[94:95]
	s_mov_b32 m0, s26
	ds_read_b128 v[174:177], v145 offset:49152
	ds_read_b128 v[178:181], v145 offset:50176
	ds_read_b128 v[182:185], v145 offset:51200
	ds_read_b128 v[186:189], v145 offset:52224
	ds_read_b128 v[190:193], v145 offset:53248
	ds_read_b128 v[194:197], v145 offset:54272
	ds_read_b128 v[198:201], v145 offset:55296
	ds_read_b128 v[202:205], v145 offset:56320
	global_load_lds_dwordx4 v[142:143], off
	s_add_i32 m0, s26, 0x2000
	s_add_u32 s24, s24, 0x40080
	v_lshl_add_u64 v[142:143], v[206:207], 0, s[94:95]
	s_addc_u32 s25, s25, 0
	s_add_i32 s26, s52, s36
	global_load_lds_dwordx4 v[142:143], off
	v_lshl_add_u64 v[142:143], s[24:25], 0, v[232:233]
	s_mov_b32 m0, s26
	s_nop 0
	global_load_lds_dwordx4 v[142:143], off
	v_lshl_add_u64 v[142:143], s[24:25], 0, v[132:133]
	s_add_i32 m0, s26, 0x2000
	s_nop 0
	global_load_lds_dwordx4 v[142:143], off
	v_lshl_add_u64 v[142:143], v[208:209], 0, s[94:95]
	s_mov_b32 m0, s43
	s_nop 0
	global_load_lds_dwordx4 v[142:143], off
	v_lshl_add_u64 v[142:143], v[210:211], 0, s[94:95]
	s_mov_b32 m0, s44
	s_nop 0
	global_load_lds_dwordx4 v[142:143], off
	s_waitcnt vmcnt(8)
	s_waitcnt lgkmcnt(0)
	s_barrier
	s_setprio 1
	s_waitcnt lgkmcnt(0)
	v_mfma_f32_16x16x32_bf16 v[60:63], v[138:141], v[174:177], v[60:63]
	v_mfma_f32_16x16x32_bf16 v[56:59], v[150:153], v[174:177], v[56:59]
	v_mfma_f32_16x16x32_bf16 v[48:51], v[138:141], v[182:185], v[48:51]
	v_mfma_f32_16x16x32_bf16 v[40:43], v[150:153], v[182:185], v[40:43]
	v_mfma_f32_16x16x32_bf16 v[32:35], v[138:141], v[190:193], v[32:35]
	v_mfma_f32_16x16x32_bf16 v[24:27], v[150:153], v[190:193], v[24:27]
	v_mfma_f32_16x16x32_bf16 v[16:19], v[138:141], v[198:201], v[16:19]
	v_mfma_f32_16x16x32_bf16 v[8:11], v[150:153], v[198:201], v[8:11]
	v_mfma_f32_16x16x32_bf16 v[60:63], v[146:149], v[178:181], v[60:63]
	v_mfma_f32_16x16x32_bf16 v[56:59], v[154:157], v[178:181], v[56:59]
	v_mfma_f32_16x16x32_bf16 v[48:51], v[146:149], v[186:189], v[48:51]
	v_mfma_f32_16x16x32_bf16 v[40:43], v[154:157], v[186:189], v[40:43]
	v_mfma_f32_16x16x32_bf16 v[32:35], v[146:149], v[194:197], v[32:35]
	v_mfma_f32_16x16x32_bf16 v[24:27], v[154:157], v[194:197], v[24:27]
	v_mfma_f32_16x16x32_bf16 v[16:19], v[146:149], v[202:205], v[16:19]
	v_mfma_f32_16x16x32_bf16 v[8:11], v[154:157], v[202:205], v[8:11]
	s_setprio 0
	s_setprio 1
	v_mfma_f32_16x16x32_bf16 v[52:55], v[158:161], v[174:177], v[52:55]
	v_mfma_f32_16x16x32_bf16 v[44:47], v[166:169], v[174:177], v[44:47]
	v_mfma_f32_16x16x32_bf16 v[36:39], v[158:161], v[182:185], v[36:39]
	v_mfma_f32_16x16x32_bf16 v[28:31], v[166:169], v[182:185], v[28:31]
	v_mfma_f32_16x16x32_bf16 v[20:23], v[158:161], v[190:193], v[20:23]
	v_mfma_f32_16x16x32_bf16 v[12:15], v[166:169], v[190:193], v[12:15]
	v_mfma_f32_16x16x32_bf16 v[4:7], v[158:161], v[198:201], v[4:7]
	v_mfma_f32_16x16x32_bf16 v[0:3], v[166:169], v[198:201], v[0:3]
	v_mfma_f32_16x16x32_bf16 v[52:55], v[162:165], v[178:181], v[52:55]
	v_mfma_f32_16x16x32_bf16 v[44:47], v[170:173], v[178:181], v[44:47]
	v_mfma_f32_16x16x32_bf16 v[36:39], v[162:165], v[186:189], v[36:39]
	v_mfma_f32_16x16x32_bf16 v[28:31], v[170:173], v[186:189], v[28:31]
	v_mfma_f32_16x16x32_bf16 v[20:23], v[162:165], v[194:197], v[20:23]
	v_mfma_f32_16x16x32_bf16 v[12:15], v[170:173], v[194:197], v[12:15]
	v_mfma_f32_16x16x32_bf16 v[4:7], v[162:165], v[202:205], v[4:7]
	v_mfma_f32_16x16x32_bf16 v[0:3], v[170:173], v[202:205], v[0:3]
	s_setprio 0
	s_barrier
	s_add_i32 s50, s50, 2
	s_add_u32 s48, s48, 0x100
	s_addc_u32 s49, s49, 0
	s_add_u32 s22, s22, 0x100
	s_addc_u32 s23, s23, 0
	s_cmp_gt_u32 s50, 13
	s_cbranch_scc0 .LBB0_188
	s_and_b64 vcc, exec, s[10:11]
	s_cbranch_vccz .LBB0_191
	s_barrier

.LBB0_912:
	s_add_u32 s24, s22, 0xfffc0080
	s_addc_u32 s25, s23, -1
	s_add_i32 s51, 0, 0x10000
	s_cmp_eq_u32 s50, 12
	s_cselect_b32 s27, s5, s25
	s_cselect_b32 s26, s15, s24
	v_add_u32_e32 v142, s51, v144
	s_cselect_b32 s25, s13, s49
	s_cselect_b32 s24, s21, s48
	s_add_i32 s54, 0, 0x14000
	ds_read_b128 v[138:141], v142
	ds_read_b128 v[146:149], v142 offset:1024
	ds_read_b128 v[150:153], v142 offset:2048
	ds_read_b128 v[154:157], v142 offset:3072
	v_add_u32_e32 v142, s54, v144
	ds_read_b128 v[158:161], v142
	ds_read_b128 v[162:165], v142 offset:1024
	ds_read_b128 v[166:169], v142 offset:2048
	ds_read_b128 v[170:173], v142 offset:3072
	v_lshl_add_u64 v[142:143], s[22:23], 0, v[136:137]
	s_add_i32 m0, s37, 0xc000
	ds_read_b128 v[174:177], v145
	ds_read_b128 v[178:181], v145 offset:1024
	ds_read_b128 v[182:185], v145 offset:2048
	ds_read_b128 v[186:189], v145 offset:3072
	ds_read_b128 v[190:193], v145 offset:4096
	ds_read_b128 v[194:197], v145 offset:5120
	ds_read_b128 v[198:201], v145 offset:6144
	ds_read_b128 v[202:205], v145 offset:7168
	global_load_lds_dwordx4 v[142:143], off
	v_lshl_add_u64 v[142:143], s[22:23], 0, v[134:135]
	s_add_i32 m0, s37, 0xe000
	s_nop 0
	global_load_lds_dwordx4 v[142:143], off
	s_waitcnt vmcnt(8)
	s_waitcnt lgkmcnt(0)
	s_barrier
	s_setprio 1
	s_waitcnt lgkmcnt(0)
	v_mfma_f32_16x16x32_bf16 v[124:127], v[138:141], v[174:177], v[124:127]
	v_mfma_f32_16x16x32_bf16 v[120:123], v[150:153], v[174:177], v[120:123]
	v_mfma_f32_16x16x32_bf16 v[108:111], v[138:141], v[182:185], v[108:111]
	v_mfma_f32_16x16x32_bf16 v[104:107], v[150:153], v[182:185], v[104:107]
	v_mfma_f32_16x16x32_bf16 v[92:95], v[138:141], v[190:193], v[92:95]
	v_mfma_f32_16x16x32_bf16 v[88:91], v[150:153], v[190:193], v[88:91]
	v_mfma_f32_16x16x32_bf16 v[76:79], v[138:141], v[198:201], v[76:79]
	v_mfma_f32_16x16x32_bf16 v[72:75], v[150:153], v[198:201], v[72:75]
	v_mfma_f32_16x16x32_bf16 v[124:127], v[146:149], v[178:181], v[124:127]
	v_mfma_f32_16x16x32_bf16 v[120:123], v[154:157], v[178:181], v[120:123]
	v_mfma_f32_16x16x32_bf16 v[108:111], v[146:149], v[186:189], v[108:111]
	v_mfma_f32_16x16x32_bf16 v[104:107], v[154:157], v[186:189], v[104:107]
	v_mfma_f32_16x16x32_bf16 v[92:95], v[146:149], v[194:197], v[92:95]
	v_mfma_f32_16x16x32_bf16 v[88:91], v[154:157], v[194:197], v[88:91]
	v_mfma_f32_16x16x32_bf16 v[76:79], v[146:149], v[202:205], v[76:79]
	v_mfma_f32_16x16x32_bf16 v[72:75], v[154:157], v[202:205], v[72:75]
	s_setprio 0
	s_setprio 1
	v_mfma_f32_16x16x32_bf16 v[116:119], v[158:161], v[174:177], v[116:119]
	v_mfma_f32_16x16x32_bf16 v[112:115], v[166:169], v[174:177], v[112:115]
	v_mfma_f32_16x16x32_bf16 v[100:103], v[158:161], v[182:185], v[100:103]
	v_mfma_f32_16x16x32_bf16 v[96:99], v[166:169], v[182:185], v[96:99]
	v_mfma_f32_16x16x32_bf16 v[84:87], v[158:161], v[190:193], v[84:87]
	v_mfma_f32_16x16x32_bf16 v[80:83], v[166:169], v[190:193], v[80:83]
	v_mfma_f32_16x16x32_bf16 v[68:71], v[158:161], v[198:201], v[68:71]
	v_mfma_f32_16x16x32_bf16 v[64:67], v[166:169], v[198:201], v[64:67]
	v_mfma_f32_16x16x32_bf16 v[116:119], v[162:165], v[178:181], v[116:119]
	v_mfma_f32_16x16x32_bf16 v[112:115], v[170:173], v[178:181], v[112:115]
	v_mfma_f32_16x16x32_bf16 v[100:103], v[162:165], v[186:189], v[100:103]
	v_mfma_f32_16x16x32_bf16 v[96:99], v[170:173], v[186:189], v[96:99]
	v_mfma_f32_16x16x32_bf16 v[84:87], v[162:165], v[194:197], v[84:87]
	v_mfma_f32_16x16x32_bf16 v[80:83], v[170:173], v[194:197], v[80:83]
	v_mfma_f32_16x16x32_bf16 v[68:71], v[162:165], v[202:205], v[68:71]
	v_mfma_f32_16x16x32_bf16 v[64:67], v[170:173], v[202:205], v[64:67]
	s_setprio 0
	s_barrier
	s_add_i32 s51, s51, s36
	v_lshl_add_u64 v[142:143], s[24:25], 0, v[232:233]
	s_mov_b32 m0, s51
	ds_read_b128 v[174:177], v145 offset:16384
	ds_read_b128 v[178:181], v145 offset:17408
	ds_read_b128 v[182:185], v145 offset:18432
	ds_read_b128 v[186:189], v145 offset:19456
	ds_read_b128 v[190:193], v145 offset:20480
	ds_read_b128 v[194:197], v145 offset:21504
	ds_read_b128 v[198:201], v145 offset:22528
	ds_read_b128 v[202:205], v145 offset:23552
	global_load_lds_dwordx4 v[142:143], off
	s_add_i32 m0, s51, 0x2000
	s_add_u32 s52, s24, 0x40000
	v_lshl_add_u64 v[206:207], s[24:25], 0, v[132:133]
	s_addc_u32 s53, s25, 0
	s_add_i32 s51, s54, s36
	global_load_lds_dwordx4 v[206:207], off
	v_lshl_add_u64 v[208:209], s[52:53], 0, v[232:233]
	s_mov_b32 m0, s51
	v_lshl_add_u64 v[210:211], s[26:27], 0, v[130:131]
	global_load_lds_dwordx4 v[208:209], off
	v_lshl_add_u64 v[208:209], s[52:53], 0, v[132:133]
	s_add_i32 m0, s51, 0x2000
	s_nop 0
	global_load_lds_dwordx4 v[208:209], off
	v_lshl_add_u64 v[208:209], s[26:27], 0, v[128:129]
	s_waitcnt vmcnt(6)
	s_waitcnt lgkmcnt(0)
	s_barrier
	s_setprio 1
	s_waitcnt lgkmcnt(0)
	v_mfma_f32_16x16x32_bf16 v[60:63], v[138:141], v[174:177], v[60:63]
	v_mfma_f32_16x16x32_bf16 v[56:59], v[150:153], v[174:177], v[56:59]
	v_mfma_f32_16x16x32_bf16 v[44:47], v[138:141], v[182:185], v[44:47]
	v_mfma_f32_16x16x32_bf16 v[40:43], v[150:153], v[182:185], v[40:43]
	v_mfma_f32_16x16x32_bf16 v[28:31], v[138:141], v[190:193], v[28:31]
	v_mfma_f32_16x16x32_bf16 v[24:27], v[150:153], v[190:193], v[24:27]
	v_mfma_f32_16x16x32_bf16 v[12:15], v[138:141], v[198:201], v[12:15]
	v_mfma_f32_16x16x32_bf16 v[8:11], v[150:153], v[198:201], v[8:11]
	v_mfma_f32_16x16x32_bf16 v[60:63], v[146:149], v[178:181], v[60:63]
	v_mfma_f32_16x16x32_bf16 v[56:59], v[154:157], v[178:181], v[56:59]
	v_mfma_f32_16x16x32_bf16 v[44:47], v[146:149], v[186:189], v[44:47]
	v_mfma_f32_16x16x32_bf16 v[40:43], v[154:157], v[186:189], v[40:43]
	v_mfma_f32_16x16x32_bf16 v[28:31], v[146:149], v[194:197], v[28:31]
	v_mfma_f32_16x16x32_bf16 v[24:27], v[154:157], v[194:197], v[24:27]
	v_mfma_f32_16x16x32_bf16 v[12:15], v[146:149], v[202:205], v[12:15]
	v_mfma_f32_16x16x32_bf16 v[8:11], v[154:157], v[202:205], v[8:11]
	s_setprio 0
	s_setprio 1
	v_mfma_f32_16x16x32_bf16 v[52:55], v[158:161], v[174:177], v[52:55]
	v_mfma_f32_16x16x32_bf16 v[48:51], v[166:169], v[174:177], v[48:51]
	v_mfma_f32_16x16x32_bf16 v[36:39], v[158:161], v[182:185], v[36:39]
	v_mfma_f32_16x16x32_bf16 v[32:35], v[166:169], v[182:185], v[32:35]
	v_mfma_f32_16x16x32_bf16 v[20:23], v[158:161], v[190:193], v[20:23]
	v_mfma_f32_16x16x32_bf16 v[16:19], v[166:169], v[190:193], v[16:19]
	v_mfma_f32_16x16x32_bf16 v[4:7], v[158:161], v[198:201], v[4:7]
	v_mfma_f32_16x16x32_bf16 v[0:3], v[166:169], v[198:201], v[0:3]
	v_mfma_f32_16x16x32_bf16 v[52:55], v[162:165], v[178:181], v[52:55]
	v_mfma_f32_16x16x32_bf16 v[48:51], v[170:173], v[178:181], v[48:51]
	v_mfma_f32_16x16x32_bf16 v[36:39], v[162:165], v[186:189], v[36:39]
	v_mfma_f32_16x16x32_bf16 v[32:35], v[170:173], v[186:189], v[32:35]
	v_mfma_f32_16x16x32_bf16 v[20:23], v[162:165], v[194:197], v[20:23]
	v_mfma_f32_16x16x32_bf16 v[16:19], v[170:173], v[194:197], v[16:19]
	v_mfma_f32_16x16x32_bf16 v[4:7], v[162:165], v[202:205], v[4:7]
	v_mfma_f32_16x16x32_bf16 v[0:3], v[170:173], v[202:205], v[0:3]
	s_setprio 0
	s_barrier
	s_add_i32 s51, 0, 0x18000
	s_add_i32 s52, 0, 0x1c000
	v_add_u32_e32 v154, s51, v144
	v_add_u32_e32 v170, s52, v144
	ds_read_b128 v[138:141], v154
	ds_read_b128 v[146:149], v154 offset:1024
	ds_read_b128 v[150:153], v154 offset:2048
	ds_read_b128 v[154:157], v154 offset:3072
	ds_read_b128 v[158:161], v170
	ds_read_b128 v[162:165], v170 offset:1024
	ds_read_b128 v[166:169], v170 offset:2048
	ds_read_b128 v[170:173], v170 offset:3072
	s_add_u32 s26, s26, 0x40000
	s_addc_u32 s27, s27, 0
	s_mov_b32 m0, s37
	s_nop 0
	global_load_lds_dwordx4 v[208:209], off
	s_mov_b32 m0, s38
	s_nop 0
	global_load_lds_dwordx4 v[210:211], off
	s_mov_b32 m0, s39
	v_lshl_add_u64 v[212:213], s[26:27], 0, v[128:129]
	ds_read_b128 v[174:177], v145 offset:32768
	ds_read_b128 v[178:181], v145 offset:33792
	ds_read_b128 v[182:185], v145 offset:34816
	ds_read_b128 v[186:189], v145 offset:35840
	ds_read_b128 v[190:193], v145 offset:36864
	ds_read_b128 v[194:197], v145 offset:37888
	ds_read_b128 v[198:201], v145 offset:38912
	ds_read_b128 v[202:205], v145 offset:39936
	global_load_lds_dwordx4 v[212:213], off
	v_lshl_add_u64 v[212:213], s[26:27], 0, v[130:131]
	s_mov_b32 m0, s40
	s_nop 0
	global_load_lds_dwordx4 v[212:213], off
	s_waitcnt vmcnt(8)
	s_waitcnt lgkmcnt(0)
	s_barrier
	s_setprio 1
	s_waitcnt lgkmcnt(0)
	v_mfma_f32_16x16x32_bf16 v[124:127], v[138:141], v[174:177], v[124:127]
	v_mfma_f32_16x16x32_bf16 v[120:123], v[150:153], v[174:177], v[120:123]
	v_mfma_f32_16x16x32_bf16 v[108:111], v[138:141], v[182:185], v[108:111]
	v_mfma_f32_16x16x32_bf16 v[104:107], v[150:153], v[182:185], v[104:107]
	v_mfma_f32_16x16x32_bf16 v[92:95], v[138:141], v[190:193], v[92:95]
	v_mfma_f32_16x16x32_bf16 v[88:91], v[150:153], v[190:193], v[88:91]
	v_mfma_f32_16x16x32_bf16 v[76:79], v[138:141], v[198:201], v[76:79]
	v_mfma_f32_16x16x32_bf16 v[72:75], v[150:153], v[198:201], v[72:75]
	v_mfma_f32_16x16x32_bf16 v[124:127], v[146:149], v[178:181], v[124:127]
	v_mfma_f32_16x16x32_bf16 v[120:123], v[154:157], v[178:181], v[120:123]
	v_mfma_f32_16x16x32_bf16 v[108:111], v[146:149], v[186:189], v[108:111]
	v_mfma_f32_16x16x32_bf16 v[104:107], v[154:157], v[186:189], v[104:107]
	v_mfma_f32_16x16x32_bf16 v[92:95], v[146:149], v[194:197], v[92:95]
	v_mfma_f32_16x16x32_bf16 v[88:91], v[154:157], v[194:197], v[88:91]
	v_mfma_f32_16x16x32_bf16 v[76:79], v[146:149], v[202:205], v[76:79]
	v_mfma_f32_16x16x32_bf16 v[72:75], v[154:157], v[202:205], v[72:75]
	s_setprio 0
	s_setprio 1
	v_mfma_f32_16x16x32_bf16 v[116:119], v[158:161], v[174:177], v[116:119]
	v_mfma_f32_16x16x32_bf16 v[112:115], v[166:169], v[174:177], v[112:115]
	v_mfma_f32_16x16x32_bf16 v[100:103], v[158:161], v[182:185], v[100:103]
	v_mfma_f32_16x16x32_bf16 v[96:99], v[166:169], v[182:185], v[96:99]
	v_mfma_f32_16x16x32_bf16 v[84:87], v[158:161], v[190:193], v[84:87]
	v_mfma_f32_16x16x32_bf16 v[80:83], v[166:169], v[190:193], v[80:83]
	v_mfma_f32_16x16x32_bf16 v[68:71], v[158:161], v[198:201], v[68:71]
	v_mfma_f32_16x16x32_bf16 v[64:67], v[166:169], v[198:201], v[64:67]
	v_mfma_f32_16x16x32_bf16 v[116:119], v[162:165], v[178:181], v[116:119]
	v_mfma_f32_16x16x32_bf16 v[112:115], v[170:173], v[178:181], v[112:115]
	v_mfma_f32_16x16x32_bf16 v[100:103], v[162:165], v[186:189], v[100:103]
	v_mfma_f32_16x16x32_bf16 v[96:99], v[170:173], v[186:189], v[96:99]
	v_mfma_f32_16x16x32_bf16 v[84:87], v[162:165], v[194:197], v[84:87]
	v_mfma_f32_16x16x32_bf16 v[80:83], v[170:173], v[194:197], v[80:83]
	v_mfma_f32_16x16x32_bf16 v[68:71], v[162:165], v[202:205], v[68:71]
	v_mfma_f32_16x16x32_bf16 v[64:67], v[170:173], v[202:205], v[64:67]
	s_setprio 0
	s_barrier
	s_add_i32 s26, s51, s36
	v_lshl_add_u64 v[142:143], v[142:143], 0, s[94:95]
	s_mov_b32 m0, s26
	ds_read_b128 v[174:177], v145 offset:49152
	ds_read_b128 v[178:181], v145 offset:50176
	ds_read_b128 v[182:185], v145 offset:51200
	ds_read_b128 v[186:189], v145 offset:52224
	ds_read_b128 v[190:193], v145 offset:53248
	ds_read_b128 v[194:197], v145 offset:54272
	ds_read_b128 v[198:201], v145 offset:55296
	ds_read_b128 v[202:205], v145 offset:56320
	global_load_lds_dwordx4 v[142:143], off
	s_add_i32 m0, s26, 0x2000
	s_add_u32 s24, s24, 0x40080
	v_lshl_add_u64 v[142:143], v[206:207], 0, s[94:95]
	s_addc_u32 s25, s25, 0
	s_add_i32 s26, s52, s36
	global_load_lds_dwordx4 v[142:143], off
	v_lshl_add_u64 v[142:143], s[24:25], 0, v[232:233]
	s_mov_b32 m0, s26
	s_nop 0
	global_load_lds_dwordx4 v[142:143], off
	v_lshl_add_u64 v[142:143], s[24:25], 0, v[132:133]
	s_add_i32 m0, s26, 0x2000
	s_nop 0
	global_load_lds_dwordx4 v[142:143], off
	v_lshl_add_u64 v[142:143], v[208:209], 0, s[94:95]
	s_mov_b32 m0, s43
	s_nop 0
	global_load_lds_dwordx4 v[142:143], off
	v_lshl_add_u64 v[142:143], v[210:211], 0, s[94:95]
	s_mov_b32 m0, s44
	s_nop 0
	global_load_lds_dwordx4 v[142:143], off
	s_waitcnt vmcnt(8)
	s_waitcnt lgkmcnt(0)
	s_barrier
	s_setprio 1
	s_waitcnt lgkmcnt(0)
	v_mfma_f32_16x16x32_bf16 v[60:63], v[138:141], v[174:177], v[60:63]
	v_mfma_f32_16x16x32_bf16 v[56:59], v[150:153], v[174:177], v[56:59]
	v_mfma_f32_16x16x32_bf16 v[44:47], v[138:141], v[182:185], v[44:47]
	v_mfma_f32_16x16x32_bf16 v[40:43], v[150:153], v[182:185], v[40:43]
	v_mfma_f32_16x16x32_bf16 v[28:31], v[138:141], v[190:193], v[28:31]
	v_mfma_f32_16x16x32_bf16 v[24:27], v[150:153], v[190:193], v[24:27]
	v_mfma_f32_16x16x32_bf16 v[12:15], v[138:141], v[198:201], v[12:15]
	v_mfma_f32_16x16x32_bf16 v[8:11], v[150:153], v[198:201], v[8:11]
	v_mfma_f32_16x16x32_bf16 v[60:63], v[146:149], v[178:181], v[60:63]
	v_mfma_f32_16x16x32_bf16 v[56:59], v[154:157], v[178:181], v[56:59]
	v_mfma_f32_16x16x32_bf16 v[44:47], v[146:149], v[186:189], v[44:47]
	v_mfma_f32_16x16x32_bf16 v[40:43], v[154:157], v[186:189], v[40:43]
	v_mfma_f32_16x16x32_bf16 v[28:31], v[146:149], v[194:197], v[28:31]
	v_mfma_f32_16x16x32_bf16 v[24:27], v[154:157], v[194:197], v[24:27]
	v_mfma_f32_16x16x32_bf16 v[12:15], v[146:149], v[202:205], v[12:15]
	v_mfma_f32_16x16x32_bf16 v[8:11], v[154:157], v[202:205], v[8:11]
	s_setprio 0
	s_setprio 1
	v_mfma_f32_16x16x32_bf16 v[52:55], v[158:161], v[174:177], v[52:55]
	v_mfma_f32_16x16x32_bf16 v[48:51], v[166:169], v[174:177], v[48:51]
	v_mfma_f32_16x16x32_bf16 v[36:39], v[158:161], v[182:185], v[36:39]
	v_mfma_f32_16x16x32_bf16 v[32:35], v[166:169], v[182:185], v[32:35]
	v_mfma_f32_16x16x32_bf16 v[20:23], v[158:161], v[190:193], v[20:23]
	v_mfma_f32_16x16x32_bf16 v[16:19], v[166:169], v[190:193], v[16:19]
	v_mfma_f32_16x16x32_bf16 v[4:7], v[158:161], v[198:201], v[4:7]
	v_mfma_f32_16x16x32_bf16 v[0:3], v[166:169], v[198:201], v[0:3]
	v_mfma_f32_16x16x32_bf16 v[52:55], v[162:165], v[178:181], v[52:55]
	v_mfma_f32_16x16x32_bf16 v[48:51], v[170:173], v[178:181], v[48:51]
	v_mfma_f32_16x16x32_bf16 v[36:39], v[162:165], v[186:189], v[36:39]
	v_mfma_f32_16x16x32_bf16 v[32:35], v[170:173], v[186:189], v[32:35]
	v_mfma_f32_16x16x32_bf16 v[20:23], v[162:165], v[194:197], v[20:23]
	v_mfma_f32_16x16x32_bf16 v[16:19], v[170:173], v[194:197], v[16:19]
	v_mfma_f32_16x16x32_bf16 v[4:7], v[162:165], v[202:205], v[4:7]
	v_mfma_f32_16x16x32_bf16 v[0:3], v[170:173], v[202:205], v[0:3]
	s_setprio 0
	s_barrier
	s_add_i32 s50, s50, 2
	s_add_u32 s48, s48, 0x100
	s_addc_u32 s49, s49, 0
	s_add_u32 s22, s22, 0x100
	s_addc_u32 s23, s23, 0
	s_cmp_gt_u32 s50, 13
	s_cbranch_scc0 .LBB0_912
	s_and_b64 vcc, exec, s[10:11]
	s_cbranch_vccz .LBB0_915
	s_barrier

.LBB0_1164:
	s_add_u32 s34, s30, 0xfffc0080
	s_addc_u32 s35, s31, -1
	s_add_i32 s61, 0, 0x10000
	s_cmp_eq_u32 s60, 12
	s_cselect_b32 s37, s23, s35
	s_cselect_b32 s36, s56, s34
	s_cselect_b32 s35, s21, s59
	s_cselect_b32 s34, s57, s58
	s_add_i32 s64, 0, 0x14000
	v_add_u32_e32 v140, s61, v174
	v_add_u32_e32 v166, s64, v174
	ds_read_b128 v[128:131], v140
	ds_read_b128 v[132:135], v140 offset:1024
	ds_read_b128 v[136:139], v140 offset:2048
	ds_read_b128 v[140:143], v140 offset:3072
	ds_read_b128 v[154:157], v166
	ds_read_b128 v[158:161], v166 offset:1024
	ds_read_b128 v[162:165], v166 offset:2048
	ds_read_b128 v[166:169], v166 offset:3072
	v_lshl_add_u64 v[204:205], s[30:31], 0, v[152:153]
	s_add_i32 m0, s29, 0xc000
	ds_read_b128 v[170:173], v175
	ds_read_b128 v[176:179], v175 offset:1024
	ds_read_b128 v[180:183], v175 offset:2048
	ds_read_b128 v[184:187], v175 offset:3072
	ds_read_b128 v[188:191], v175 offset:4096
	ds_read_b128 v[192:195], v175 offset:5120
	ds_read_b128 v[196:199], v175 offset:6144
	ds_read_b128 v[200:203], v175 offset:7168
	global_load_lds_dwordx4 v[204:205], off
	v_lshl_add_u64 v[204:205], s[30:31], 0, v[150:151]
	s_add_i32 m0, s29, 0xe000
	s_nop 0
	global_load_lds_dwordx4 v[204:205], off
	s_waitcnt vmcnt(8)
	s_waitcnt lgkmcnt(0)
	s_barrier
	s_setprio 1
	s_waitcnt lgkmcnt(0)
	v_mfma_f32_16x16x32_bf16 v[124:127], v[128:131], v[170:173], v[124:127]
	v_mfma_f32_16x16x32_bf16 v[120:123], v[136:139], v[170:173], v[120:123]
	v_mfma_f32_16x16x32_bf16 v[108:111], v[128:131], v[180:183], v[108:111]
	v_mfma_f32_16x16x32_bf16 v[104:107], v[136:139], v[180:183], v[104:107]
	v_mfma_f32_16x16x32_bf16 v[92:95], v[128:131], v[188:191], v[92:95]
	v_mfma_f32_16x16x32_bf16 v[88:91], v[136:139], v[188:191], v[88:91]
	v_mfma_f32_16x16x32_bf16 v[80:83], v[128:131], v[196:199], v[80:83]
	v_mfma_f32_16x16x32_bf16 v[72:75], v[136:139], v[196:199], v[72:75]
	v_mfma_f32_16x16x32_bf16 v[124:127], v[132:135], v[176:179], v[124:127]
	v_mfma_f32_16x16x32_bf16 v[120:123], v[140:143], v[176:179], v[120:123]
	v_mfma_f32_16x16x32_bf16 v[108:111], v[132:135], v[184:187], v[108:111]
	v_mfma_f32_16x16x32_bf16 v[104:107], v[140:143], v[184:187], v[104:107]
	v_mfma_f32_16x16x32_bf16 v[92:95], v[132:135], v[192:195], v[92:95]
	v_mfma_f32_16x16x32_bf16 v[88:91], v[140:143], v[192:195], v[88:91]
	v_mfma_f32_16x16x32_bf16 v[80:83], v[132:135], v[200:203], v[80:83]
	v_mfma_f32_16x16x32_bf16 v[72:75], v[140:143], v[200:203], v[72:75]
	s_setprio 0
	s_setprio 1
	v_mfma_f32_16x16x32_bf16 v[116:119], v[154:157], v[170:173], v[116:119]
	v_mfma_f32_16x16x32_bf16 v[112:115], v[162:165], v[170:173], v[112:115]
	v_mfma_f32_16x16x32_bf16 v[100:103], v[154:157], v[180:183], v[100:103]
	v_mfma_f32_16x16x32_bf16 v[96:99], v[162:165], v[180:183], v[96:99]
	v_mfma_f32_16x16x32_bf16 v[84:87], v[154:157], v[188:191], v[84:87]
	v_mfma_f32_16x16x32_bf16 v[76:79], v[162:165], v[188:191], v[76:79]
	v_mfma_f32_16x16x32_bf16 v[68:71], v[154:157], v[196:199], v[68:71]
	v_mfma_f32_16x16x32_bf16 v[64:67], v[162:165], v[196:199], v[64:67]
	v_mfma_f32_16x16x32_bf16 v[116:119], v[158:161], v[176:179], v[116:119]
	v_mfma_f32_16x16x32_bf16 v[112:115], v[166:169], v[176:179], v[112:115]
	v_mfma_f32_16x16x32_bf16 v[100:103], v[158:161], v[184:187], v[100:103]
	v_mfma_f32_16x16x32_bf16 v[96:99], v[166:169], v[184:187], v[96:99]
	v_mfma_f32_16x16x32_bf16 v[84:87], v[158:161], v[192:195], v[84:87]
	v_mfma_f32_16x16x32_bf16 v[76:79], v[166:169], v[192:195], v[76:79]
	v_mfma_f32_16x16x32_bf16 v[68:71], v[158:161], v[200:203], v[68:71]
	v_mfma_f32_16x16x32_bf16 v[64:67], v[166:169], v[200:203], v[64:67]
	s_setprio 0
	s_barrier
	s_add_i32 s61, s61, s41
	v_lshl_add_u64 v[204:205], s[34:35], 0, v[232:233]
	s_mov_b32 m0, s61
	ds_read_b128 v[170:173], v175 offset:16384
	ds_read_b128 v[176:179], v175 offset:17408
	ds_read_b128 v[180:183], v175 offset:18432
	ds_read_b128 v[184:187], v175 offset:19456
	ds_read_b128 v[188:191], v175 offset:20480
	ds_read_b128 v[192:195], v175 offset:21504
	ds_read_b128 v[196:199], v175 offset:22528
	ds_read_b128 v[200:203], v175 offset:23552
	global_load_lds_dwordx4 v[204:205], off
	s_add_i32 m0, s61, 0x2000
	s_add_u32 s62, s34, 0x40000
	v_lshl_add_u64 v[206:207], s[34:35], 0, v[148:149]
	s_addc_u32 s63, s35, 0
	s_add_i32 s61, s64, s41
	global_load_lds_dwordx4 v[206:207], off
	v_lshl_add_u64 v[208:209], s[62:63], 0, v[232:233]
	s_mov_b32 m0, s61
	v_lshl_add_u64 v[210:211], s[36:37], 0, v[146:147]
	global_load_lds_dwordx4 v[208:209], off
	v_lshl_add_u64 v[208:209], s[62:63], 0, v[148:149]
	s_add_i32 m0, s61, 0x2000
	s_nop 0
	global_load_lds_dwordx4 v[208:209], off
	v_lshl_add_u64 v[208:209], s[36:37], 0, v[144:145]
	s_waitcnt vmcnt(6)
	s_waitcnt lgkmcnt(0)
	s_barrier
	s_setprio 1
	s_waitcnt lgkmcnt(0)
	v_mfma_f32_16x16x32_bf16 v[60:63], v[128:131], v[170:173], v[60:63]
	v_mfma_f32_16x16x32_bf16 v[56:59], v[136:139], v[170:173], v[56:59]
	v_mfma_f32_16x16x32_bf16 v[48:51], v[128:131], v[180:183], v[48:51]
	v_mfma_f32_16x16x32_bf16 v[40:43], v[136:139], v[180:183], v[40:43]
	v_mfma_f32_16x16x32_bf16 v[28:31], v[128:131], v[188:191], v[28:31]
	v_mfma_f32_16x16x32_bf16 v[24:27], v[136:139], v[188:191], v[24:27]
	v_mfma_f32_16x16x32_bf16 v[16:19], v[128:131], v[196:199], v[16:19]
	v_mfma_f32_16x16x32_bf16 v[8:11], v[136:139], v[196:199], v[8:11]
	v_mfma_f32_16x16x32_bf16 v[60:63], v[132:135], v[176:179], v[60:63]
	v_mfma_f32_16x16x32_bf16 v[56:59], v[140:143], v[176:179], v[56:59]
	v_mfma_f32_16x16x32_bf16 v[48:51], v[132:135], v[184:187], v[48:51]
	v_mfma_f32_16x16x32_bf16 v[40:43], v[140:143], v[184:187], v[40:43]
	v_mfma_f32_16x16x32_bf16 v[28:31], v[132:135], v[192:195], v[28:31]
	v_mfma_f32_16x16x32_bf16 v[24:27], v[140:143], v[192:195], v[24:27]
	v_mfma_f32_16x16x32_bf16 v[16:19], v[132:135], v[200:203], v[16:19]
	v_mfma_f32_16x16x32_bf16 v[8:11], v[140:143], v[200:203], v[8:11]
	s_setprio 0
	s_setprio 1
	v_mfma_f32_16x16x32_bf16 v[52:55], v[154:157], v[170:173], v[52:55]
	v_mfma_f32_16x16x32_bf16 v[44:47], v[162:165], v[170:173], v[44:47]
	v_mfma_f32_16x16x32_bf16 v[36:39], v[154:157], v[180:183], v[36:39]
	v_mfma_f32_16x16x32_bf16 v[32:35], v[162:165], v[180:183], v[32:35]
	v_mfma_f32_16x16x32_bf16 v[20:23], v[154:157], v[188:191], v[20:23]
	v_mfma_f32_16x16x32_bf16 v[12:15], v[162:165], v[188:191], v[12:15]
	v_mfma_f32_16x16x32_bf16 v[4:7], v[154:157], v[196:199], v[4:7]
	v_mfma_f32_16x16x32_bf16 v[0:3], v[162:165], v[196:199], v[0:3]
	v_mfma_f32_16x16x32_bf16 v[52:55], v[158:161], v[176:179], v[52:55]
	v_mfma_f32_16x16x32_bf16 v[44:47], v[166:169], v[176:179], v[44:47]
	v_mfma_f32_16x16x32_bf16 v[36:39], v[158:161], v[184:187], v[36:39]
	v_mfma_f32_16x16x32_bf16 v[32:35], v[166:169], v[184:187], v[32:35]
	v_mfma_f32_16x16x32_bf16 v[20:23], v[158:161], v[192:195], v[20:23]
	v_mfma_f32_16x16x32_bf16 v[12:15], v[166:169], v[192:195], v[12:15]
	v_mfma_f32_16x16x32_bf16 v[4:7], v[158:161], v[200:203], v[4:7]
	v_mfma_f32_16x16x32_bf16 v[0:3], v[166:169], v[200:203], v[0:3]
	s_setprio 0
	s_barrier
	s_add_i32 s61, 0, 0x18000
	s_add_i32 s62, 0, 0x1c000
	v_add_u32_e32 v140, s61, v174
	v_add_u32_e32 v166, s62, v174
	ds_read_b128 v[128:131], v140
	ds_read_b128 v[132:135], v140 offset:1024
	ds_read_b128 v[136:139], v140 offset:2048
	ds_read_b128 v[140:143], v140 offset:3072
	ds_read_b128 v[154:157], v166
	ds_read_b128 v[158:161], v166 offset:1024
	ds_read_b128 v[162:165], v166 offset:2048
	ds_read_b128 v[166:169], v166 offset:3072
	s_add_u32 s36, s36, 0x40000
	s_addc_u32 s37, s37, 0
	s_mov_b32 m0, s29
	s_nop 0
	global_load_lds_dwordx4 v[208:209], off
	s_mov_b32 m0, s46
	s_nop 0
	global_load_lds_dwordx4 v[210:211], off
	s_mov_b32 m0, s47
	v_lshl_add_u64 v[212:213], s[36:37], 0, v[144:145]
	ds_read_b128 v[170:173], v175 offset:32768
	ds_read_b128 v[176:179], v175 offset:33792
	ds_read_b128 v[180:183], v175 offset:34816
	ds_read_b128 v[184:187], v175 offset:35840
	ds_read_b128 v[188:191], v175 offset:36864
	ds_read_b128 v[192:195], v175 offset:37888
	ds_read_b128 v[196:199], v175 offset:38912
	ds_read_b128 v[200:203], v175 offset:39936
	global_load_lds_dwordx4 v[212:213], off
	v_lshl_add_u64 v[212:213], s[36:37], 0, v[146:147]
	s_mov_b32 m0, s48
	s_nop 0
	global_load_lds_dwordx4 v[212:213], off
	s_waitcnt vmcnt(8)
	s_waitcnt lgkmcnt(0)
	s_barrier
	s_setprio 1
	s_waitcnt lgkmcnt(0)
	v_mfma_f32_16x16x32_bf16 v[124:127], v[128:131], v[170:173], v[124:127]
	v_mfma_f32_16x16x32_bf16 v[120:123], v[136:139], v[170:173], v[120:123]
	v_mfma_f32_16x16x32_bf16 v[108:111], v[128:131], v[180:183], v[108:111]
	v_mfma_f32_16x16x32_bf16 v[104:107], v[136:139], v[180:183], v[104:107]
	v_mfma_f32_16x16x32_bf16 v[92:95], v[128:131], v[188:191], v[92:95]
	v_mfma_f32_16x16x32_bf16 v[88:91], v[136:139], v[188:191], v[88:91]
	v_mfma_f32_16x16x32_bf16 v[80:83], v[128:131], v[196:199], v[80:83]
	v_mfma_f32_16x16x32_bf16 v[72:75], v[136:139], v[196:199], v[72:75]
	v_mfma_f32_16x16x32_bf16 v[124:127], v[132:135], v[176:179], v[124:127]
	v_mfma_f32_16x16x32_bf16 v[120:123], v[140:143], v[176:179], v[120:123]
	v_mfma_f32_16x16x32_bf16 v[108:111], v[132:135], v[184:187], v[108:111]
	v_mfma_f32_16x16x32_bf16 v[104:107], v[140:143], v[184:187], v[104:107]
	v_mfma_f32_16x16x32_bf16 v[92:95], v[132:135], v[192:195], v[92:95]
	v_mfma_f32_16x16x32_bf16 v[88:91], v[140:143], v[192:195], v[88:91]
	v_mfma_f32_16x16x32_bf16 v[80:83], v[132:135], v[200:203], v[80:83]
	v_mfma_f32_16x16x32_bf16 v[72:75], v[140:143], v[200:203], v[72:75]
	s_setprio 0
	s_setprio 1
	v_mfma_f32_16x16x32_bf16 v[116:119], v[154:157], v[170:173], v[116:119]
	v_mfma_f32_16x16x32_bf16 v[112:115], v[162:165], v[170:173], v[112:115]
	v_mfma_f32_16x16x32_bf16 v[100:103], v[154:157], v[180:183], v[100:103]
	v_mfma_f32_16x16x32_bf16 v[96:99], v[162:165], v[180:183], v[96:99]
	v_mfma_f32_16x16x32_bf16 v[84:87], v[154:157], v[188:191], v[84:87]
	v_mfma_f32_16x16x32_bf16 v[76:79], v[162:165], v[188:191], v[76:79]
	v_mfma_f32_16x16x32_bf16 v[68:71], v[154:157], v[196:199], v[68:71]
	v_mfma_f32_16x16x32_bf16 v[64:67], v[162:165], v[196:199], v[64:67]
	v_mfma_f32_16x16x32_bf16 v[116:119], v[158:161], v[176:179], v[116:119]
	v_mfma_f32_16x16x32_bf16 v[112:115], v[166:169], v[176:179], v[112:115]
	v_mfma_f32_16x16x32_bf16 v[100:103], v[158:161], v[184:187], v[100:103]
	v_mfma_f32_16x16x32_bf16 v[96:99], v[166:169], v[184:187], v[96:99]
	v_mfma_f32_16x16x32_bf16 v[84:87], v[158:161], v[192:195], v[84:87]
	v_mfma_f32_16x16x32_bf16 v[76:79], v[166:169], v[192:195], v[76:79]
	v_mfma_f32_16x16x32_bf16 v[68:71], v[158:161], v[200:203], v[68:71]
	v_mfma_f32_16x16x32_bf16 v[64:67], v[166:169], v[200:203], v[64:67]
	s_setprio 0
	s_barrier
	s_add_i32 s36, s61, s41
	v_lshl_add_u64 v[204:205], v[204:205], 0, s[94:95]
	s_mov_b32 m0, s36
	ds_read_b128 v[170:173], v175 offset:49152
	ds_read_b128 v[176:179], v175 offset:50176
	ds_read_b128 v[180:183], v175 offset:51200
	ds_read_b128 v[184:187], v175 offset:52224
	ds_read_b128 v[188:191], v175 offset:53248
	ds_read_b128 v[192:195], v175 offset:54272
	ds_read_b128 v[196:199], v175 offset:55296
	ds_read_b128 v[200:203], v175 offset:56320
	global_load_lds_dwordx4 v[204:205], off
	s_add_i32 m0, s36, 0x2000
	s_add_u32 s34, s34, 0x40080
	v_lshl_add_u64 v[204:205], v[206:207], 0, s[94:95]
	s_addc_u32 s35, s35, 0
	s_add_i32 s36, s62, s41
	global_load_lds_dwordx4 v[204:205], off
	v_lshl_add_u64 v[204:205], s[34:35], 0, v[232:233]
	s_mov_b32 m0, s36
	s_nop 0
	global_load_lds_dwordx4 v[204:205], off
	v_lshl_add_u64 v[204:205], s[34:35], 0, v[148:149]
	s_add_i32 m0, s36, 0x2000
	s_nop 0
	global_load_lds_dwordx4 v[204:205], off
	v_lshl_add_u64 v[204:205], v[208:209], 0, s[94:95]
	s_mov_b32 m0, s51
	s_nop 0
	global_load_lds_dwordx4 v[204:205], off
	v_lshl_add_u64 v[204:205], v[210:211], 0, s[94:95]
	s_mov_b32 m0, s52
	s_nop 0
	global_load_lds_dwordx4 v[204:205], off
	s_waitcnt vmcnt(8)
	s_waitcnt lgkmcnt(0)
	s_barrier
	s_setprio 1
	s_waitcnt lgkmcnt(0)
	v_mfma_f32_16x16x32_bf16 v[60:63], v[128:131], v[170:173], v[60:63]
	v_mfma_f32_16x16x32_bf16 v[56:59], v[136:139], v[170:173], v[56:59]
	v_mfma_f32_16x16x32_bf16 v[48:51], v[128:131], v[180:183], v[48:51]
	v_mfma_f32_16x16x32_bf16 v[40:43], v[136:139], v[180:183], v[40:43]
	v_mfma_f32_16x16x32_bf16 v[28:31], v[128:131], v[188:191], v[28:31]
	v_mfma_f32_16x16x32_bf16 v[24:27], v[136:139], v[188:191], v[24:27]
	v_mfma_f32_16x16x32_bf16 v[16:19], v[128:131], v[196:199], v[16:19]
	v_mfma_f32_16x16x32_bf16 v[8:11], v[136:139], v[196:199], v[8:11]
	v_mfma_f32_16x16x32_bf16 v[60:63], v[132:135], v[176:179], v[60:63]
	v_mfma_f32_16x16x32_bf16 v[56:59], v[140:143], v[176:179], v[56:59]
	v_mfma_f32_16x16x32_bf16 v[48:51], v[132:135], v[184:187], v[48:51]
	v_mfma_f32_16x16x32_bf16 v[40:43], v[140:143], v[184:187], v[40:43]
	v_mfma_f32_16x16x32_bf16 v[28:31], v[132:135], v[192:195], v[28:31]
	v_mfma_f32_16x16x32_bf16 v[24:27], v[140:143], v[192:195], v[24:27]
	v_mfma_f32_16x16x32_bf16 v[16:19], v[132:135], v[200:203], v[16:19]
	v_mfma_f32_16x16x32_bf16 v[8:11], v[140:143], v[200:203], v[8:11]
	s_setprio 0
	s_setprio 1
	v_mfma_f32_16x16x32_bf16 v[52:55], v[154:157], v[170:173], v[52:55]
	v_mfma_f32_16x16x32_bf16 v[44:47], v[162:165], v[170:173], v[44:47]
	v_mfma_f32_16x16x32_bf16 v[36:39], v[154:157], v[180:183], v[36:39]
	v_mfma_f32_16x16x32_bf16 v[32:35], v[162:165], v[180:183], v[32:35]
	v_mfma_f32_16x16x32_bf16 v[20:23], v[154:157], v[188:191], v[20:23]
	v_mfma_f32_16x16x32_bf16 v[12:15], v[162:165], v[188:191], v[12:15]
	v_mfma_f32_16x16x32_bf16 v[4:7], v[154:157], v[196:199], v[4:7]
	v_mfma_f32_16x16x32_bf16 v[0:3], v[162:165], v[196:199], v[0:3]
	v_mfma_f32_16x16x32_bf16 v[52:55], v[158:161], v[176:179], v[52:55]
	v_mfma_f32_16x16x32_bf16 v[44:47], v[166:169], v[176:179], v[44:47]
	v_mfma_f32_16x16x32_bf16 v[36:39], v[158:161], v[184:187], v[36:39]
	v_mfma_f32_16x16x32_bf16 v[32:35], v[166:169], v[184:187], v[32:35]
	v_mfma_f32_16x16x32_bf16 v[20:23], v[158:161], v[192:195], v[20:23]
	v_mfma_f32_16x16x32_bf16 v[12:15], v[166:169], v[192:195], v[12:15]
	v_mfma_f32_16x16x32_bf16 v[4:7], v[158:161], v[200:203], v[4:7]
	v_mfma_f32_16x16x32_bf16 v[0:3], v[166:169], v[200:203], v[0:3]
	s_setprio 0
	s_barrier
	s_add_i32 s60, s60, 2
	s_add_u32 s58, s58, 0x100
	s_addc_u32 s59, s59, 0
	s_add_u32 s30, s30, 0x100
	s_addc_u32 s31, s31, 0
	s_cmp_gt_u32 s60, 13
	s_cbranch_scc0 .LBB0_1164
	s_and_b64 vcc, exec, s[18:19]
	s_cbranch_vccz .LBB0_1167
	s_barrier

.LBB0_1307:
	s_add_u32 s26, s24, 0xfffc0080
	s_addc_u32 s27, s25, -1
	s_add_i32 s53, 0, 0x10000
	s_cmp_eq_u32 s52, 12
	s_cselect_b32 s29, s7, s27
	s_cselect_b32 s28, s17, s26
	v_add_u32_e32 v142, s53, v144
	s_cselect_b32 s27, s15, s51
	s_cselect_b32 s26, s23, s50
	s_add_i32 s56, 0, 0x14000
	ds_read_b128 v[138:141], v142
	ds_read_b128 v[146:149], v142 offset:1024
	ds_read_b128 v[150:153], v142 offset:2048
	ds_read_b128 v[154:157], v142 offset:3072
	v_add_u32_e32 v142, s56, v144
	ds_read_b128 v[158:161], v142
	ds_read_b128 v[162:165], v142 offset:1024
	ds_read_b128 v[166:169], v142 offset:2048
	ds_read_b128 v[170:173], v142 offset:3072
	v_lshl_add_u64 v[142:143], s[24:25], 0, v[136:137]
	s_add_i32 m0, s39, 0xc000
	ds_read_b128 v[174:177], v145
	ds_read_b128 v[178:181], v145 offset:1024
	ds_read_b128 v[182:185], v145 offset:2048
	ds_read_b128 v[186:189], v145 offset:3072
	ds_read_b128 v[190:193], v145 offset:4096
	ds_read_b128 v[194:197], v145 offset:5120
	ds_read_b128 v[198:201], v145 offset:6144
	ds_read_b128 v[202:205], v145 offset:7168
	global_load_lds_dwordx4 v[142:143], off
	v_lshl_add_u64 v[142:143], s[24:25], 0, v[134:135]
	s_add_i32 m0, s39, 0xe000
	s_nop 0
	global_load_lds_dwordx4 v[142:143], off
	s_waitcnt vmcnt(8)
	s_waitcnt lgkmcnt(0)
	s_barrier
	s_setprio 1
	s_waitcnt lgkmcnt(0)
	v_mfma_f32_16x16x32_bf16 v[124:127], v[138:141], v[174:177], v[124:127]
	v_mfma_f32_16x16x32_bf16 v[120:123], v[150:153], v[174:177], v[120:123]
	v_mfma_f32_16x16x32_bf16 v[108:111], v[138:141], v[182:185], v[108:111]
	v_mfma_f32_16x16x32_bf16 v[104:107], v[150:153], v[182:185], v[104:107]
	v_mfma_f32_16x16x32_bf16 v[92:95], v[138:141], v[190:193], v[92:95]
	v_mfma_f32_16x16x32_bf16 v[88:91], v[150:153], v[190:193], v[88:91]
	v_mfma_f32_16x16x32_bf16 v[76:79], v[138:141], v[198:201], v[76:79]
	v_mfma_f32_16x16x32_bf16 v[72:75], v[150:153], v[198:201], v[72:75]
	v_mfma_f32_16x16x32_bf16 v[124:127], v[146:149], v[178:181], v[124:127]
	v_mfma_f32_16x16x32_bf16 v[120:123], v[154:157], v[178:181], v[120:123]
	v_mfma_f32_16x16x32_bf16 v[108:111], v[146:149], v[186:189], v[108:111]
	v_mfma_f32_16x16x32_bf16 v[104:107], v[154:157], v[186:189], v[104:107]
	v_mfma_f32_16x16x32_bf16 v[92:95], v[146:149], v[194:197], v[92:95]
	v_mfma_f32_16x16x32_bf16 v[88:91], v[154:157], v[194:197], v[88:91]
	v_mfma_f32_16x16x32_bf16 v[76:79], v[146:149], v[202:205], v[76:79]
	v_mfma_f32_16x16x32_bf16 v[72:75], v[154:157], v[202:205], v[72:75]
	s_setprio 0
	s_setprio 1
	v_mfma_f32_16x16x32_bf16 v[116:119], v[158:161], v[174:177], v[116:119]
	v_mfma_f32_16x16x32_bf16 v[112:115], v[166:169], v[174:177], v[112:115]
	v_mfma_f32_16x16x32_bf16 v[100:103], v[158:161], v[182:185], v[100:103]
	v_mfma_f32_16x16x32_bf16 v[96:99], v[166:169], v[182:185], v[96:99]
	v_mfma_f32_16x16x32_bf16 v[84:87], v[158:161], v[190:193], v[84:87]
	v_mfma_f32_16x16x32_bf16 v[80:83], v[166:169], v[190:193], v[80:83]
	v_mfma_f32_16x16x32_bf16 v[68:71], v[158:161], v[198:201], v[68:71]
	v_mfma_f32_16x16x32_bf16 v[64:67], v[166:169], v[198:201], v[64:67]
	v_mfma_f32_16x16x32_bf16 v[116:119], v[162:165], v[178:181], v[116:119]
	v_mfma_f32_16x16x32_bf16 v[112:115], v[170:173], v[178:181], v[112:115]
	v_mfma_f32_16x16x32_bf16 v[100:103], v[162:165], v[186:189], v[100:103]
	v_mfma_f32_16x16x32_bf16 v[96:99], v[170:173], v[186:189], v[96:99]
	v_mfma_f32_16x16x32_bf16 v[84:87], v[162:165], v[194:197], v[84:87]
	v_mfma_f32_16x16x32_bf16 v[80:83], v[170:173], v[194:197], v[80:83]
	v_mfma_f32_16x16x32_bf16 v[68:71], v[162:165], v[202:205], v[68:71]
	v_mfma_f32_16x16x32_bf16 v[64:67], v[170:173], v[202:205], v[64:67]
	s_setprio 0
	s_barrier
	s_add_i32 s53, s53, s38
	v_lshl_add_u64 v[142:143], s[26:27], 0, v[232:233]
	s_mov_b32 m0, s53
	ds_read_b128 v[174:177], v145 offset:16384
	ds_read_b128 v[178:181], v145 offset:17408
	ds_read_b128 v[182:185], v145 offset:18432
	ds_read_b128 v[186:189], v145 offset:19456
	ds_read_b128 v[190:193], v145 offset:20480
	ds_read_b128 v[194:197], v145 offset:21504
	ds_read_b128 v[198:201], v145 offset:22528
	ds_read_b128 v[202:205], v145 offset:23552
	global_load_lds_dwordx4 v[142:143], off
	s_add_i32 m0, s53, 0x2000
	s_add_u32 s54, s26, 0x40000
	v_lshl_add_u64 v[206:207], s[26:27], 0, v[132:133]
	s_addc_u32 s55, s27, 0
	s_add_i32 s53, s56, s38
	global_load_lds_dwordx4 v[206:207], off
	v_lshl_add_u64 v[208:209], s[54:55], 0, v[232:233]
	s_mov_b32 m0, s53
	v_lshl_add_u64 v[210:211], s[28:29], 0, v[130:131]
	global_load_lds_dwordx4 v[208:209], off
	v_lshl_add_u64 v[208:209], s[54:55], 0, v[132:133]
	s_add_i32 m0, s53, 0x2000
	s_nop 0
	global_load_lds_dwordx4 v[208:209], off
	v_lshl_add_u64 v[208:209], s[28:29], 0, v[128:129]
	s_waitcnt vmcnt(6)
	s_waitcnt lgkmcnt(0)
	s_barrier
	s_setprio 1
	s_waitcnt lgkmcnt(0)
	v_mfma_f32_16x16x32_bf16 v[60:63], v[138:141], v[174:177], v[60:63]
	v_mfma_f32_16x16x32_bf16 v[56:59], v[150:153], v[174:177], v[56:59]
	v_mfma_f32_16x16x32_bf16 v[44:47], v[138:141], v[182:185], v[44:47]
	v_mfma_f32_16x16x32_bf16 v[40:43], v[150:153], v[182:185], v[40:43]
	v_mfma_f32_16x16x32_bf16 v[28:31], v[138:141], v[190:193], v[28:31]
	v_mfma_f32_16x16x32_bf16 v[24:27], v[150:153], v[190:193], v[24:27]
	v_mfma_f32_16x16x32_bf16 v[12:15], v[138:141], v[198:201], v[12:15]
	v_mfma_f32_16x16x32_bf16 v[8:11], v[150:153], v[198:201], v[8:11]
	v_mfma_f32_16x16x32_bf16 v[60:63], v[146:149], v[178:181], v[60:63]
	v_mfma_f32_16x16x32_bf16 v[56:59], v[154:157], v[178:181], v[56:59]
	v_mfma_f32_16x16x32_bf16 v[44:47], v[146:149], v[186:189], v[44:47]
	v_mfma_f32_16x16x32_bf16 v[40:43], v[154:157], v[186:189], v[40:43]
	v_mfma_f32_16x16x32_bf16 v[28:31], v[146:149], v[194:197], v[28:31]
	v_mfma_f32_16x16x32_bf16 v[24:27], v[154:157], v[194:197], v[24:27]
	v_mfma_f32_16x16x32_bf16 v[12:15], v[146:149], v[202:205], v[12:15]
	v_mfma_f32_16x16x32_bf16 v[8:11], v[154:157], v[202:205], v[8:11]
	s_setprio 0
	s_setprio 1
	v_mfma_f32_16x16x32_bf16 v[52:55], v[158:161], v[174:177], v[52:55]
	v_mfma_f32_16x16x32_bf16 v[48:51], v[166:169], v[174:177], v[48:51]
	v_mfma_f32_16x16x32_bf16 v[36:39], v[158:161], v[182:185], v[36:39]
	v_mfma_f32_16x16x32_bf16 v[32:35], v[166:169], v[182:185], v[32:35]
	v_mfma_f32_16x16x32_bf16 v[20:23], v[158:161], v[190:193], v[20:23]
	v_mfma_f32_16x16x32_bf16 v[16:19], v[166:169], v[190:193], v[16:19]
	v_mfma_f32_16x16x32_bf16 v[4:7], v[158:161], v[198:201], v[4:7]
	v_mfma_f32_16x16x32_bf16 v[0:3], v[166:169], v[198:201], v[0:3]
	v_mfma_f32_16x16x32_bf16 v[52:55], v[162:165], v[178:181], v[52:55]
	v_mfma_f32_16x16x32_bf16 v[48:51], v[170:173], v[178:181], v[48:51]
	v_mfma_f32_16x16x32_bf16 v[36:39], v[162:165], v[186:189], v[36:39]
	v_mfma_f32_16x16x32_bf16 v[32:35], v[170:173], v[186:189], v[32:35]
	v_mfma_f32_16x16x32_bf16 v[20:23], v[162:165], v[194:197], v[20:23]
	v_mfma_f32_16x16x32_bf16 v[16:19], v[170:173], v[194:197], v[16:19]
	v_mfma_f32_16x16x32_bf16 v[4:7], v[162:165], v[202:205], v[4:7]
	v_mfma_f32_16x16x32_bf16 v[0:3], v[170:173], v[202:205], v[0:3]
	s_setprio 0
	s_barrier
	s_add_i32 s53, 0, 0x18000
	s_add_i32 s54, 0, 0x1c000
	v_add_u32_e32 v154, s53, v144
	v_add_u32_e32 v170, s54, v144
	ds_read_b128 v[138:141], v154
	ds_read_b128 v[146:149], v154 offset:1024
	ds_read_b128 v[150:153], v154 offset:2048
	ds_read_b128 v[154:157], v154 offset:3072
	ds_read_b128 v[158:161], v170
	ds_read_b128 v[162:165], v170 offset:1024
	ds_read_b128 v[166:169], v170 offset:2048
	ds_read_b128 v[170:173], v170 offset:3072
	s_add_u32 s28, s28, 0x40000
	s_addc_u32 s29, s29, 0
	s_mov_b32 m0, s39
	s_nop 0
	global_load_lds_dwordx4 v[208:209], off
	s_mov_b32 m0, s40
	s_nop 0
	global_load_lds_dwordx4 v[210:211], off
	s_mov_b32 m0, s41
	v_lshl_add_u64 v[212:213], s[28:29], 0, v[128:129]
	ds_read_b128 v[174:177], v145 offset:32768
	ds_read_b128 v[178:181], v145 offset:33792
	ds_read_b128 v[182:185], v145 offset:34816
	ds_read_b128 v[186:189], v145 offset:35840
	ds_read_b128 v[190:193], v145 offset:36864
	ds_read_b128 v[194:197], v145 offset:37888
	ds_read_b128 v[198:201], v145 offset:38912
	ds_read_b128 v[202:205], v145 offset:39936
	global_load_lds_dwordx4 v[212:213], off
	v_lshl_add_u64 v[212:213], s[28:29], 0, v[130:131]
	s_mov_b32 m0, s42
	s_nop 0
	global_load_lds_dwordx4 v[212:213], off
	s_waitcnt vmcnt(8)
	s_waitcnt lgkmcnt(0)
	s_barrier
	s_setprio 1
	s_waitcnt lgkmcnt(0)
	v_mfma_f32_16x16x32_bf16 v[124:127], v[138:141], v[174:177], v[124:127]
	v_mfma_f32_16x16x32_bf16 v[120:123], v[150:153], v[174:177], v[120:123]
	v_mfma_f32_16x16x32_bf16 v[108:111], v[138:141], v[182:185], v[108:111]
	v_mfma_f32_16x16x32_bf16 v[104:107], v[150:153], v[182:185], v[104:107]
	v_mfma_f32_16x16x32_bf16 v[92:95], v[138:141], v[190:193], v[92:95]
	v_mfma_f32_16x16x32_bf16 v[88:91], v[150:153], v[190:193], v[88:91]
	v_mfma_f32_16x16x32_bf16 v[76:79], v[138:141], v[198:201], v[76:79]
	v_mfma_f32_16x16x32_bf16 v[72:75], v[150:153], v[198:201], v[72:75]
	v_mfma_f32_16x16x32_bf16 v[124:127], v[146:149], v[178:181], v[124:127]
	v_mfma_f32_16x16x32_bf16 v[120:123], v[154:157], v[178:181], v[120:123]
	v_mfma_f32_16x16x32_bf16 v[108:111], v[146:149], v[186:189], v[108:111]
	v_mfma_f32_16x16x32_bf16 v[104:107], v[154:157], v[186:189], v[104:107]
	v_mfma_f32_16x16x32_bf16 v[92:95], v[146:149], v[194:197], v[92:95]
	v_mfma_f32_16x16x32_bf16 v[88:91], v[154:157], v[194:197], v[88:91]
	v_mfma_f32_16x16x32_bf16 v[76:79], v[146:149], v[202:205], v[76:79]
	v_mfma_f32_16x16x32_bf16 v[72:75], v[154:157], v[202:205], v[72:75]
	s_setprio 0
	s_setprio 1
	v_mfma_f32_16x16x32_bf16 v[116:119], v[158:161], v[174:177], v[116:119]
	v_mfma_f32_16x16x32_bf16 v[112:115], v[166:169], v[174:177], v[112:115]
	v_mfma_f32_16x16x32_bf16 v[100:103], v[158:161], v[182:185], v[100:103]
	v_mfma_f32_16x16x32_bf16 v[96:99], v[166:169], v[182:185], v[96:99]
	v_mfma_f32_16x16x32_bf16 v[84:87], v[158:161], v[190:193], v[84:87]
	v_mfma_f32_16x16x32_bf16 v[80:83], v[166:169], v[190:193], v[80:83]
	v_mfma_f32_16x16x32_bf16 v[68:71], v[158:161], v[198:201], v[68:71]
	v_mfma_f32_16x16x32_bf16 v[64:67], v[166:169], v[198:201], v[64:67]
	v_mfma_f32_16x16x32_bf16 v[116:119], v[162:165], v[178:181], v[116:119]
	v_mfma_f32_16x16x32_bf16 v[112:115], v[170:173], v[178:181], v[112:115]
	v_mfma_f32_16x16x32_bf16 v[100:103], v[162:165], v[186:189], v[100:103]
	v_mfma_f32_16x16x32_bf16 v[96:99], v[170:173], v[186:189], v[96:99]
	v_mfma_f32_16x16x32_bf16 v[84:87], v[162:165], v[194:197], v[84:87]
	v_mfma_f32_16x16x32_bf16 v[80:83], v[170:173], v[194:197], v[80:83]
	v_mfma_f32_16x16x32_bf16 v[68:71], v[162:165], v[202:205], v[68:71]
	v_mfma_f32_16x16x32_bf16 v[64:67], v[170:173], v[202:205], v[64:67]
	s_setprio 0
	s_barrier
	s_add_i32 s28, s53, s38
	v_lshl_add_u64 v[142:143], v[142:143], 0, s[94:95]
	s_mov_b32 m0, s28
	ds_read_b128 v[174:177], v145 offset:49152
	ds_read_b128 v[178:181], v145 offset:50176
	ds_read_b128 v[182:185], v145 offset:51200
	ds_read_b128 v[186:189], v145 offset:52224
	ds_read_b128 v[190:193], v145 offset:53248
	ds_read_b128 v[194:197], v145 offset:54272
	ds_read_b128 v[198:201], v145 offset:55296
	ds_read_b128 v[202:205], v145 offset:56320
	global_load_lds_dwordx4 v[142:143], off
	s_add_i32 m0, s28, 0x2000
	s_add_u32 s26, s26, 0x40080
	v_lshl_add_u64 v[142:143], v[206:207], 0, s[94:95]
	s_addc_u32 s27, s27, 0
	s_add_i32 s28, s54, s38
	global_load_lds_dwordx4 v[142:143], off
	v_lshl_add_u64 v[142:143], s[26:27], 0, v[232:233]
	s_mov_b32 m0, s28
	s_nop 0
	global_load_lds_dwordx4 v[142:143], off
	v_lshl_add_u64 v[142:143], s[26:27], 0, v[132:133]
	s_add_i32 m0, s28, 0x2000
	s_nop 0
	global_load_lds_dwordx4 v[142:143], off
	v_lshl_add_u64 v[142:143], v[208:209], 0, s[94:95]
	s_mov_b32 m0, s45
	s_nop 0
	global_load_lds_dwordx4 v[142:143], off
	v_lshl_add_u64 v[142:143], v[210:211], 0, s[94:95]
	s_mov_b32 m0, s46
	s_nop 0
	global_load_lds_dwordx4 v[142:143], off
	s_waitcnt vmcnt(8)
	s_waitcnt lgkmcnt(0)
	s_barrier
	s_setprio 1
	s_waitcnt lgkmcnt(0)
	v_mfma_f32_16x16x32_bf16 v[60:63], v[138:141], v[174:177], v[60:63]
	v_mfma_f32_16x16x32_bf16 v[56:59], v[150:153], v[174:177], v[56:59]
	v_mfma_f32_16x16x32_bf16 v[44:47], v[138:141], v[182:185], v[44:47]
	v_mfma_f32_16x16x32_bf16 v[40:43], v[150:153], v[182:185], v[40:43]
	v_mfma_f32_16x16x32_bf16 v[28:31], v[138:141], v[190:193], v[28:31]
	v_mfma_f32_16x16x32_bf16 v[24:27], v[150:153], v[190:193], v[24:27]
	v_mfma_f32_16x16x32_bf16 v[12:15], v[138:141], v[198:201], v[12:15]
	v_mfma_f32_16x16x32_bf16 v[8:11], v[150:153], v[198:201], v[8:11]
	v_mfma_f32_16x16x32_bf16 v[60:63], v[146:149], v[178:181], v[60:63]
	v_mfma_f32_16x16x32_bf16 v[56:59], v[154:157], v[178:181], v[56:59]
	v_mfma_f32_16x16x32_bf16 v[44:47], v[146:149], v[186:189], v[44:47]
	v_mfma_f32_16x16x32_bf16 v[40:43], v[154:157], v[186:189], v[40:43]
	v_mfma_f32_16x16x32_bf16 v[28:31], v[146:149], v[194:197], v[28:31]
	v_mfma_f32_16x16x32_bf16 v[24:27], v[154:157], v[194:197], v[24:27]
	v_mfma_f32_16x16x32_bf16 v[12:15], v[146:149], v[202:205], v[12:15]
	v_mfma_f32_16x16x32_bf16 v[8:11], v[154:157], v[202:205], v[8:11]
	s_setprio 0
	s_setprio 1
	v_mfma_f32_16x16x32_bf16 v[52:55], v[158:161], v[174:177], v[52:55]
	v_mfma_f32_16x16x32_bf16 v[48:51], v[166:169], v[174:177], v[48:51]
	v_mfma_f32_16x16x32_bf16 v[36:39], v[158:161], v[182:185], v[36:39]
	v_mfma_f32_16x16x32_bf16 v[32:35], v[166:169], v[182:185], v[32:35]
	v_mfma_f32_16x16x32_bf16 v[20:23], v[158:161], v[190:193], v[20:23]
	v_mfma_f32_16x16x32_bf16 v[16:19], v[166:169], v[190:193], v[16:19]
	v_mfma_f32_16x16x32_bf16 v[4:7], v[158:161], v[198:201], v[4:7]
	v_mfma_f32_16x16x32_bf16 v[0:3], v[166:169], v[198:201], v[0:3]
	v_mfma_f32_16x16x32_bf16 v[52:55], v[162:165], v[178:181], v[52:55]
	v_mfma_f32_16x16x32_bf16 v[48:51], v[170:173], v[178:181], v[48:51]
	v_mfma_f32_16x16x32_bf16 v[36:39], v[162:165], v[186:189], v[36:39]
	v_mfma_f32_16x16x32_bf16 v[32:35], v[170:173], v[186:189], v[32:35]
	v_mfma_f32_16x16x32_bf16 v[20:23], v[162:165], v[194:197], v[20:23]
	v_mfma_f32_16x16x32_bf16 v[16:19], v[170:173], v[194:197], v[16:19]
	v_mfma_f32_16x16x32_bf16 v[4:7], v[162:165], v[202:205], v[4:7]
	v_mfma_f32_16x16x32_bf16 v[0:3], v[170:173], v[202:205], v[0:3]
	s_setprio 0
	s_barrier
	s_add_i32 s52, s52, 2
	s_add_u32 s50, s50, 0x100
	s_addc_u32 s51, s51, 0
	s_add_u32 s24, s24, 0x100
	s_addc_u32 s25, s25, 0
	s_cmp_gt_u32 s52, 13
	s_cbranch_scc0 .LBB0_1307
	s_and_b64 vcc, exec, s[12:13]
	s_cbranch_vccz .LBB0_1310
	s_barrier

.LBB0_1492:
	s_add_u32 s34, s30, 0xfff00080
	s_addc_u32 s35, s31, -1
	s_add_i32 s61, 0, 0x10000
	s_cmp_eq_u32 s60, 60
	s_cselect_b32 s37, s23, s35
	s_cselect_b32 s36, s56, s34
	s_cselect_b32 s35, s21, s59
	s_cselect_b32 s34, s57, s58
	s_add_i32 s64, 0, 0x14000
	v_add_u32_e32 v100, s61, v220
	v_add_u32_e32 v156, s64, v220
	ds_read_b128 v[88:91], v100
	ds_read_b128 v[92:95], v100 offset:1024
	ds_read_b128 v[96:99], v100 offset:2048
	ds_read_b128 v[100:103], v100 offset:3072
	ds_read_b128 v[144:147], v156
	ds_read_b128 v[148:151], v156 offset:1024
	ds_read_b128 v[152:155], v156 offset:2048
	ds_read_b128 v[156:159], v156 offset:3072
	v_lshl_add_u64 v[202:203], s[30:31], 0, v[188:189]
	s_add_i32 m0, s78, 0xc000
	ds_read_b128 v[160:163], v221
	ds_read_b128 v[164:167], v221 offset:1024
	ds_read_b128 v[168:171], v221 offset:2048
	ds_read_b128 v[172:175], v221 offset:3072
	ds_read_b128 v[176:179], v221 offset:4096
	ds_read_b128 v[190:193], v221 offset:5120
	ds_read_b128 v[194:197], v221 offset:6144
	ds_read_b128 v[198:201], v221 offset:7168
	global_load_lds_dwordx4 v[202:203], off
	v_lshl_add_u64 v[202:203], s[30:31], 0, v[186:187]
	s_add_i32 m0, s78, 0xe000
	s_nop 0
	global_load_lds_dwordx4 v[202:203], off
	s_waitcnt vmcnt(8)
	s_waitcnt lgkmcnt(0)
	s_barrier
	s_setprio 1
	s_waitcnt lgkmcnt(0)
	v_mfma_f32_16x16x32_bf16 v[140:143], v[88:91], v[160:163], v[140:143]
	v_mfma_f32_16x16x32_bf16 v[136:139], v[96:99], v[160:163], v[136:139]
	v_mfma_f32_16x16x32_bf16 v[124:127], v[88:91], v[168:171], v[124:127]
	v_mfma_f32_16x16x32_bf16 v[120:123], v[96:99], v[168:171], v[120:123]
	v_mfma_f32_16x16x32_bf16 v[108:111], v[88:91], v[176:179], v[108:111]
	v_mfma_f32_16x16x32_bf16 v[104:107], v[96:99], v[176:179], v[104:107]
	v_mfma_f32_16x16x32_bf16 v[76:79], v[88:91], v[194:197], v[76:79]
	v_mfma_f32_16x16x32_bf16 v[72:75], v[96:99], v[194:197], v[72:75]
	v_mfma_f32_16x16x32_bf16 v[140:143], v[92:95], v[164:167], v[140:143]
	v_mfma_f32_16x16x32_bf16 v[136:139], v[100:103], v[164:167], v[136:139]
	v_mfma_f32_16x16x32_bf16 v[124:127], v[92:95], v[172:175], v[124:127]
	v_mfma_f32_16x16x32_bf16 v[120:123], v[100:103], v[172:175], v[120:123]
	v_mfma_f32_16x16x32_bf16 v[108:111], v[92:95], v[190:193], v[108:111]
	v_mfma_f32_16x16x32_bf16 v[104:107], v[100:103], v[190:193], v[104:107]
	v_mfma_f32_16x16x32_bf16 v[76:79], v[92:95], v[198:201], v[76:79]
	v_mfma_f32_16x16x32_bf16 v[72:75], v[100:103], v[198:201], v[72:75]
	s_setprio 0
	s_setprio 1
	v_mfma_f32_16x16x32_bf16 v[132:135], v[144:147], v[160:163], v[132:135]
	v_mfma_f32_16x16x32_bf16 v[128:131], v[152:155], v[160:163], v[128:131]
	v_mfma_f32_16x16x32_bf16 v[116:119], v[144:147], v[168:171], v[116:119]
	v_mfma_f32_16x16x32_bf16 v[112:115], v[152:155], v[168:171], v[112:115]
	v_mfma_f32_16x16x32_bf16 v[84:87], v[144:147], v[176:179], v[84:87]
	v_mfma_f32_16x16x32_bf16 v[80:83], v[152:155], v[176:179], v[80:83]
	v_mfma_f32_16x16x32_bf16 v[68:71], v[144:147], v[194:197], v[68:71]
	v_mfma_f32_16x16x32_bf16 v[64:67], v[152:155], v[194:197], v[64:67]
	v_mfma_f32_16x16x32_bf16 v[132:135], v[148:151], v[164:167], v[132:135]
	v_mfma_f32_16x16x32_bf16 v[128:131], v[156:159], v[164:167], v[128:131]
	v_mfma_f32_16x16x32_bf16 v[116:119], v[148:151], v[172:175], v[116:119]
	v_mfma_f32_16x16x32_bf16 v[112:115], v[156:159], v[172:175], v[112:115]
	v_mfma_f32_16x16x32_bf16 v[84:87], v[148:151], v[190:193], v[84:87]
	v_mfma_f32_16x16x32_bf16 v[80:83], v[156:159], v[190:193], v[80:83]
	v_mfma_f32_16x16x32_bf16 v[68:71], v[148:151], v[198:201], v[68:71]
	v_mfma_f32_16x16x32_bf16 v[64:67], v[156:159], v[198:201], v[64:67]
	s_setprio 0
	s_barrier
	s_add_i32 s61, s61, s77
	v_lshl_add_u64 v[202:203], s[34:35], 0, v[232:233]
	s_mov_b32 m0, s61
	ds_read_b128 v[160:163], v221 offset:16384
	ds_read_b128 v[164:167], v221 offset:17408
	ds_read_b128 v[168:171], v221 offset:18432
	ds_read_b128 v[172:175], v221 offset:19456
	ds_read_b128 v[176:179], v221 offset:20480
	ds_read_b128 v[190:193], v221 offset:21504
	ds_read_b128 v[194:197], v221 offset:22528
	ds_read_b128 v[198:201], v221 offset:23552
	global_load_lds_dwordx4 v[202:203], off
	s_add_i32 m0, s61, 0x2000
	s_add_u32 s62, s34, 0x100000
	v_lshl_add_u64 v[204:205], s[34:35], 0, v[184:185]
	s_addc_u32 s63, s35, 0
	s_add_i32 s61, s64, s77
	global_load_lds_dwordx4 v[204:205], off
	v_lshl_add_u64 v[206:207], s[62:63], 0, v[232:233]
	s_mov_b32 m0, s61
	v_lshl_add_u64 v[208:209], s[36:37], 0, v[182:183]
	global_load_lds_dwordx4 v[206:207], off
	v_lshl_add_u64 v[206:207], s[62:63], 0, v[184:185]
	s_add_i32 m0, s61, 0x2000
	s_nop 0
	global_load_lds_dwordx4 v[206:207], off
	v_lshl_add_u64 v[206:207], s[36:37], 0, v[180:181]
	s_waitcnt vmcnt(6)
	s_waitcnt lgkmcnt(0)
	s_barrier
	s_setprio 1
	s_waitcnt lgkmcnt(0)
	v_mfma_f32_16x16x32_bf16 v[60:63], v[88:91], v[160:163], v[60:63]
	v_mfma_f32_16x16x32_bf16 v[56:59], v[96:99], v[160:163], v[56:59]
	v_mfma_f32_16x16x32_bf16 v[44:47], v[88:91], v[168:171], v[44:47]
	v_mfma_f32_16x16x32_bf16 v[40:43], v[96:99], v[168:171], v[40:43]
	v_mfma_f32_16x16x32_bf16 v[28:31], v[88:91], v[176:179], v[28:31]
	v_mfma_f32_16x16x32_bf16 v[24:27], v[96:99], v[176:179], v[24:27]
	v_mfma_f32_16x16x32_bf16 v[12:15], v[88:91], v[194:197], v[12:15]
	v_mfma_f32_16x16x32_bf16 v[8:11], v[96:99], v[194:197], v[8:11]
	v_mfma_f32_16x16x32_bf16 v[60:63], v[92:95], v[164:167], v[60:63]
	v_mfma_f32_16x16x32_bf16 v[56:59], v[100:103], v[164:167], v[56:59]
	v_mfma_f32_16x16x32_bf16 v[44:47], v[92:95], v[172:175], v[44:47]
	v_mfma_f32_16x16x32_bf16 v[40:43], v[100:103], v[172:175], v[40:43]
	v_mfma_f32_16x16x32_bf16 v[28:31], v[92:95], v[190:193], v[28:31]
	v_mfma_f32_16x16x32_bf16 v[24:27], v[100:103], v[190:193], v[24:27]
	v_mfma_f32_16x16x32_bf16 v[12:15], v[92:95], v[198:201], v[12:15]
	v_mfma_f32_16x16x32_bf16 v[8:11], v[100:103], v[198:201], v[8:11]
	s_setprio 0
	s_setprio 1
	v_mfma_f32_16x16x32_bf16 v[52:55], v[144:147], v[160:163], v[52:55]
	v_mfma_f32_16x16x32_bf16 v[48:51], v[152:155], v[160:163], v[48:51]
	v_mfma_f32_16x16x32_bf16 v[36:39], v[144:147], v[168:171], v[36:39]
	v_mfma_f32_16x16x32_bf16 v[32:35], v[152:155], v[168:171], v[32:35]
	v_mfma_f32_16x16x32_bf16 v[20:23], v[144:147], v[176:179], v[20:23]
	v_mfma_f32_16x16x32_bf16 v[16:19], v[152:155], v[176:179], v[16:19]
	v_mfma_f32_16x16x32_bf16 v[4:7], v[144:147], v[194:197], v[4:7]
	v_mfma_f32_16x16x32_bf16 v[0:3], v[152:155], v[194:197], v[0:3]
	v_mfma_f32_16x16x32_bf16 v[52:55], v[148:151], v[164:167], v[52:55]
	v_mfma_f32_16x16x32_bf16 v[48:51], v[156:159], v[164:167], v[48:51]
	v_mfma_f32_16x16x32_bf16 v[36:39], v[148:151], v[172:175], v[36:39]
	v_mfma_f32_16x16x32_bf16 v[32:35], v[156:159], v[172:175], v[32:35]
	v_mfma_f32_16x16x32_bf16 v[20:23], v[148:151], v[190:193], v[20:23]
	v_mfma_f32_16x16x32_bf16 v[16:19], v[156:159], v[190:193], v[16:19]
	v_mfma_f32_16x16x32_bf16 v[4:7], v[148:151], v[198:201], v[4:7]
	v_mfma_f32_16x16x32_bf16 v[0:3], v[156:159], v[198:201], v[0:3]
	s_setprio 0
	s_barrier
	s_add_i32 s61, 0, 0x18000
	s_add_i32 s62, 0, 0x1c000
	v_add_u32_e32 v100, s61, v220
	v_add_u32_e32 v156, s62, v220
	ds_read_b128 v[88:91], v100
	ds_read_b128 v[92:95], v100 offset:1024
	ds_read_b128 v[96:99], v100 offset:2048
	ds_read_b128 v[100:103], v100 offset:3072
	ds_read_b128 v[144:147], v156
	ds_read_b128 v[148:151], v156 offset:1024
	ds_read_b128 v[152:155], v156 offset:2048
	ds_read_b128 v[156:159], v156 offset:3072
	s_add_u32 s36, s36, 0x100000
	s_addc_u32 s37, s37, 0
	s_mov_b32 m0, s78
	s_nop 0
	global_load_lds_dwordx4 v[206:207], off
	s_mov_b32 m0, s79
	s_nop 0
	global_load_lds_dwordx4 v[208:209], off
	s_mov_b32 m0, s80
	v_lshl_add_u64 v[210:211], s[36:37], 0, v[180:181]
	ds_read_b128 v[160:163], v221 offset:32768
	ds_read_b128 v[164:167], v221 offset:33792
	ds_read_b128 v[168:171], v221 offset:34816
	ds_read_b128 v[172:175], v221 offset:35840
	ds_read_b128 v[176:179], v221 offset:36864
	ds_read_b128 v[190:193], v221 offset:37888
	ds_read_b128 v[194:197], v221 offset:38912
	ds_read_b128 v[198:201], v221 offset:39936
	global_load_lds_dwordx4 v[210:211], off
	v_lshl_add_u64 v[210:211], s[36:37], 0, v[182:183]
	s_mov_b32 m0, s81
	s_nop 0
	global_load_lds_dwordx4 v[210:211], off
	s_waitcnt vmcnt(8)
	s_waitcnt lgkmcnt(0)
	s_barrier
	s_setprio 1
	s_waitcnt lgkmcnt(0)
	v_mfma_f32_16x16x32_bf16 v[140:143], v[88:91], v[160:163], v[140:143]
	v_mfma_f32_16x16x32_bf16 v[136:139], v[96:99], v[160:163], v[136:139]
	v_mfma_f32_16x16x32_bf16 v[124:127], v[88:91], v[168:171], v[124:127]
	v_mfma_f32_16x16x32_bf16 v[120:123], v[96:99], v[168:171], v[120:123]
	v_mfma_f32_16x16x32_bf16 v[108:111], v[88:91], v[176:179], v[108:111]
	v_mfma_f32_16x16x32_bf16 v[104:107], v[96:99], v[176:179], v[104:107]
	v_mfma_f32_16x16x32_bf16 v[76:79], v[88:91], v[194:197], v[76:79]
	v_mfma_f32_16x16x32_bf16 v[72:75], v[96:99], v[194:197], v[72:75]
	v_mfma_f32_16x16x32_bf16 v[140:143], v[92:95], v[164:167], v[140:143]
	v_mfma_f32_16x16x32_bf16 v[136:139], v[100:103], v[164:167], v[136:139]
	v_mfma_f32_16x16x32_bf16 v[124:127], v[92:95], v[172:175], v[124:127]
	v_mfma_f32_16x16x32_bf16 v[120:123], v[100:103], v[172:175], v[120:123]
	v_mfma_f32_16x16x32_bf16 v[108:111], v[92:95], v[190:193], v[108:111]
	v_mfma_f32_16x16x32_bf16 v[104:107], v[100:103], v[190:193], v[104:107]
	v_mfma_f32_16x16x32_bf16 v[76:79], v[92:95], v[198:201], v[76:79]
	v_mfma_f32_16x16x32_bf16 v[72:75], v[100:103], v[198:201], v[72:75]
	s_setprio 0
	s_setprio 1
	v_mfma_f32_16x16x32_bf16 v[132:135], v[144:147], v[160:163], v[132:135]
	v_mfma_f32_16x16x32_bf16 v[128:131], v[152:155], v[160:163], v[128:131]
	v_mfma_f32_16x16x32_bf16 v[116:119], v[144:147], v[168:171], v[116:119]
	v_mfma_f32_16x16x32_bf16 v[112:115], v[152:155], v[168:171], v[112:115]
	v_mfma_f32_16x16x32_bf16 v[84:87], v[144:147], v[176:179], v[84:87]
	v_mfma_f32_16x16x32_bf16 v[80:83], v[152:155], v[176:179], v[80:83]
	v_mfma_f32_16x16x32_bf16 v[68:71], v[144:147], v[194:197], v[68:71]
	v_mfma_f32_16x16x32_bf16 v[64:67], v[152:155], v[194:197], v[64:67]
	v_mfma_f32_16x16x32_bf16 v[132:135], v[148:151], v[164:167], v[132:135]
	v_mfma_f32_16x16x32_bf16 v[128:131], v[156:159], v[164:167], v[128:131]
	v_mfma_f32_16x16x32_bf16 v[116:119], v[148:151], v[172:175], v[116:119]
	v_mfma_f32_16x16x32_bf16 v[112:115], v[156:159], v[172:175], v[112:115]
	v_mfma_f32_16x16x32_bf16 v[84:87], v[148:151], v[190:193], v[84:87]
	v_mfma_f32_16x16x32_bf16 v[80:83], v[156:159], v[190:193], v[80:83]
	v_mfma_f32_16x16x32_bf16 v[68:71], v[148:151], v[198:201], v[68:71]
	v_mfma_f32_16x16x32_bf16 v[64:67], v[156:159], v[198:201], v[64:67]
	s_setprio 0
	s_barrier
	s_add_i32 s36, s61, s77
	v_lshl_add_u64 v[202:203], v[202:203], 0, s[94:95]
	s_mov_b32 m0, s36
	ds_read_b128 v[160:163], v221 offset:49152
	ds_read_b128 v[164:167], v221 offset:50176
	ds_read_b128 v[168:171], v221 offset:51200
	ds_read_b128 v[172:175], v221 offset:52224
	ds_read_b128 v[176:179], v221 offset:53248
	ds_read_b128 v[190:193], v221 offset:54272
	ds_read_b128 v[194:197], v221 offset:55296
	ds_read_b128 v[198:201], v221 offset:56320
	global_load_lds_dwordx4 v[202:203], off
	s_add_i32 m0, s36, 0x2000
	s_add_u32 s34, s34, 0x100080
	v_lshl_add_u64 v[202:203], v[204:205], 0, s[94:95]
	s_addc_u32 s35, s35, 0
	s_add_i32 s36, s62, s77
	global_load_lds_dwordx4 v[202:203], off
	v_lshl_add_u64 v[202:203], s[34:35], 0, v[232:233]
	s_mov_b32 m0, s36
	s_nop 0
	global_load_lds_dwordx4 v[202:203], off
	v_lshl_add_u64 v[202:203], s[34:35], 0, v[184:185]
	s_add_i32 m0, s36, 0x2000
	s_nop 0
	global_load_lds_dwordx4 v[202:203], off
	v_lshl_add_u64 v[202:203], v[206:207], 0, s[94:95]
	s_mov_b32 m0, s52
	s_nop 0
	global_load_lds_dwordx4 v[202:203], off
	v_lshl_add_u64 v[202:203], v[208:209], 0, s[94:95]
	s_mov_b32 m0, s53
	s_nop 0
	global_load_lds_dwordx4 v[202:203], off
	s_waitcnt vmcnt(8)
	s_waitcnt lgkmcnt(0)
	s_barrier
	s_setprio 1
	s_waitcnt lgkmcnt(0)
	v_mfma_f32_16x16x32_bf16 v[60:63], v[88:91], v[160:163], v[60:63]
	v_mfma_f32_16x16x32_bf16 v[56:59], v[96:99], v[160:163], v[56:59]
	v_mfma_f32_16x16x32_bf16 v[44:47], v[88:91], v[168:171], v[44:47]
	v_mfma_f32_16x16x32_bf16 v[40:43], v[96:99], v[168:171], v[40:43]
	v_mfma_f32_16x16x32_bf16 v[28:31], v[88:91], v[176:179], v[28:31]
	v_mfma_f32_16x16x32_bf16 v[24:27], v[96:99], v[176:179], v[24:27]
	v_mfma_f32_16x16x32_bf16 v[12:15], v[88:91], v[194:197], v[12:15]
	v_mfma_f32_16x16x32_bf16 v[8:11], v[96:99], v[194:197], v[8:11]
	v_mfma_f32_16x16x32_bf16 v[60:63], v[92:95], v[164:167], v[60:63]
	v_mfma_f32_16x16x32_bf16 v[56:59], v[100:103], v[164:167], v[56:59]
	v_mfma_f32_16x16x32_bf16 v[44:47], v[92:95], v[172:175], v[44:47]
	v_mfma_f32_16x16x32_bf16 v[40:43], v[100:103], v[172:175], v[40:43]
	v_mfma_f32_16x16x32_bf16 v[28:31], v[92:95], v[190:193], v[28:31]
	v_mfma_f32_16x16x32_bf16 v[24:27], v[100:103], v[190:193], v[24:27]
	v_mfma_f32_16x16x32_bf16 v[12:15], v[92:95], v[198:201], v[12:15]
	v_mfma_f32_16x16x32_bf16 v[8:11], v[100:103], v[198:201], v[8:11]
	s_setprio 0
	s_setprio 1
	v_mfma_f32_16x16x32_bf16 v[52:55], v[144:147], v[160:163], v[52:55]
	v_mfma_f32_16x16x32_bf16 v[48:51], v[152:155], v[160:163], v[48:51]
	v_mfma_f32_16x16x32_bf16 v[36:39], v[144:147], v[168:171], v[36:39]
	v_mfma_f32_16x16x32_bf16 v[32:35], v[152:155], v[168:171], v[32:35]
	v_mfma_f32_16x16x32_bf16 v[20:23], v[144:147], v[176:179], v[20:23]
	v_mfma_f32_16x16x32_bf16 v[16:19], v[152:155], v[176:179], v[16:19]
	v_mfma_f32_16x16x32_bf16 v[4:7], v[144:147], v[194:197], v[4:7]
	v_mfma_f32_16x16x32_bf16 v[0:3], v[152:155], v[194:197], v[0:3]
	v_mfma_f32_16x16x32_bf16 v[52:55], v[148:151], v[164:167], v[52:55]
	v_mfma_f32_16x16x32_bf16 v[48:51], v[156:159], v[164:167], v[48:51]
	v_mfma_f32_16x16x32_bf16 v[36:39], v[148:151], v[172:175], v[36:39]
	v_mfma_f32_16x16x32_bf16 v[32:35], v[156:159], v[172:175], v[32:35]
	v_mfma_f32_16x16x32_bf16 v[20:23], v[148:151], v[190:193], v[20:23]
	v_mfma_f32_16x16x32_bf16 v[16:19], v[156:159], v[190:193], v[16:19]
	v_mfma_f32_16x16x32_bf16 v[4:7], v[148:151], v[198:201], v[4:7]
	v_mfma_f32_16x16x32_bf16 v[0:3], v[156:159], v[198:201], v[0:3]
	s_setprio 0
	s_barrier
	s_add_i32 s60, s60, 2
	s_add_u32 s58, s58, 0x100
	s_addc_u32 s59, s59, 0
	s_add_u32 s30, s30, 0x100
	s_addc_u32 s31, s31, 0
	s_cmp_gt_u32 s60, 61
	s_cbranch_scc0 .LBB0_1492
	s_and_b64 vcc, exec, s[18:19]
	s_cbranch_vccz .LBB0_1495
	s_barrier
